# E37: K-loop closing barrier released 8 MFMAs early (was 4), trailing MFMAs at priority 2; otherwise identical to E30
# speedup vs baseline: 1.0061x; 1.0061x over previous
.Lcm1_skip:
.LBB0_225:
	ds_read_b128 v[128:131], v157
	ds_read_b128 v[132:135], v157 offset:1024
	ds_read_b128 v[146:149], v157 offset:2048
	ds_read_b128 v[164:167], v157 offset:3072
	ds_read_b128 v[168:171], v159
	ds_read_b128 v[172:175], v159 offset:1024
	ds_read_b128 v[176:179], v159 offset:2048
	ds_read_b128 v[180:183], v159 offset:3072
	s_add_u32 s36, s22, 0xfff80080
	s_addc_u32 s37, s23, -1
	s_cmp_eq_u32 s78, 28
	s_cselect_b32 s81, s5, s37
	s_cselect_b32 s80, s14, s36
	s_cselect_b32 vcc_hi, s20, s45
	s_cselect_b32 vcc_lo, s21, s24
	s_add_i32 m0, s77, 0xc000
	ds_read_b128 v[184:187], v161
	ds_read_b128 v[188:191], v161 offset:1024
	ds_read_b128 v[192:195], v161 offset:2048
	ds_read_b128 v[196:199], v161 offset:3072
	ds_read_b128 v[200:203], v161 offset:4096
	ds_read_b128 v[204:207], v161 offset:5120
	ds_read_b128 v[208:211], v161 offset:6144
	ds_read_b128 v[212:215], v161 offset:7168
	global_load_lds_dwordx4 v140, s[22:23]
	s_add_i32 m0, s77, 0xe000
	s_nop 0
	s_add_u32 s98, s22, s6
	s_addc_u32 s99, s23, s7
	global_load_lds_dwordx4 v140, s[98:99]
	s_waitcnt vmcnt(8)
	s_waitcnt lgkmcnt(0)
	s_barrier
	s_setprio 1
	s_waitcnt lgkmcnt(0)
	v_mfma_i32_16x16x64_i8 v[0:3], v[128:131], v[184:187], v[0:3]
	v_mfma_i32_16x16x64_i8 v[0:3], v[132:135], v[188:191], v[0:3]
	v_mfma_i32_16x16x64_i8 v[56:59], v[146:149], v[184:187], v[56:59]
	v_mfma_i32_16x16x64_i8 v[56:59], v[164:167], v[188:191], v[56:59]
	v_mfma_i32_16x16x64_i8 v[4:7], v[128:131], v[192:195], v[4:7]
	v_mfma_i32_16x16x64_i8 v[4:7], v[132:135], v[196:199], v[4:7]
	v_mfma_i32_16x16x64_i8 v[52:55], v[146:149], v[192:195], v[52:55]
	v_mfma_i32_16x16x64_i8 v[52:55], v[164:167], v[196:199], v[52:55]
	v_mfma_i32_16x16x64_i8 v[12:15], v[128:131], v[200:203], v[12:15]
	v_mfma_i32_16x16x64_i8 v[12:15], v[132:135], v[204:207], v[12:15]
	v_mfma_i32_16x16x64_i8 v[48:51], v[146:149], v[200:203], v[48:51]
	v_mfma_i32_16x16x64_i8 v[48:51], v[164:167], v[204:207], v[48:51]
	v_mfma_i32_16x16x64_i8 v[8:11], v[128:131], v[208:211], v[8:11]
	v_mfma_i32_16x16x64_i8 v[8:11], v[132:135], v[212:215], v[8:11]
	v_mfma_i32_16x16x64_i8 v[44:47], v[146:149], v[208:211], v[44:47]
	v_mfma_i32_16x16x64_i8 v[44:47], v[164:167], v[212:215], v[44:47]
	s_setprio 0
	s_setprio 1
	v_mfma_i32_16x16x64_i8 v[88:91], v[168:171], v[184:187], v[88:91]
	v_mfma_i32_16x16x64_i8 v[88:91], v[172:175], v[188:191], v[88:91]
	v_mfma_i32_16x16x64_i8 v[120:123], v[176:179], v[184:187], v[120:123]
	v_mfma_i32_16x16x64_i8 v[120:123], v[180:183], v[188:191], v[120:123]
	v_mfma_i32_16x16x64_i8 v[84:87], v[168:171], v[192:195], v[84:87]
	v_mfma_i32_16x16x64_i8 v[84:87], v[172:175], v[196:199], v[84:87]
	v_mfma_i32_16x16x64_i8 v[116:119], v[176:179], v[192:195], v[116:119]
	v_mfma_i32_16x16x64_i8 v[116:119], v[180:183], v[196:199], v[116:119]
	s_setprio 2
	s_barrier
	v_mfma_i32_16x16x64_i8 v[80:83], v[168:171], v[200:203], v[80:83]
	v_mfma_i32_16x16x64_i8 v[80:83], v[172:175], v[204:207], v[80:83]
	v_mfma_i32_16x16x64_i8 v[112:115], v[176:179], v[200:203], v[112:115]
	v_mfma_i32_16x16x64_i8 v[112:115], v[180:183], v[204:207], v[112:115]
	v_mfma_i32_16x16x64_i8 v[76:79], v[168:171], v[208:211], v[76:79]
	v_mfma_i32_16x16x64_i8 v[76:79], v[172:175], v[212:215], v[76:79]
	v_mfma_i32_16x16x64_i8 v[108:111], v[176:179], v[208:211], v[108:111]
	v_mfma_i32_16x16x64_i8 v[108:111], v[180:183], v[212:215], v[108:111]
	s_setprio 0
	s_add_i32 s36, s86, s63
	s_mov_b32 m0, s36
	ds_read_b128 v[184:187], v161 offset:16384
	ds_read_b128 v[188:191], v161 offset:17408
	ds_read_b128 v[192:195], v161 offset:18432
	ds_read_b128 v[196:199], v161 offset:19456
	ds_read_b128 v[200:203], v161 offset:20480
	ds_read_b128 v[204:207], v161 offset:21504
	ds_read_b128 v[208:211], v161 offset:22528
	ds_read_b128 v[212:215], v161 offset:23552
	global_load_lds_dwordx4 v138, vcc
	s_add_i32 m0, s36, 0x2000
	s_add_i32 s36, s87, s63
	s_add_u32 s98, vcc_lo, s6
	s_addc_u32 s99, vcc_hi, s7
	global_load_lds_dwordx4 v138, s[98:99]
	s_mov_b32 m0, s36
	s_nop 0
	s_add_u32 s98, vcc_lo, s8
	s_addc_u32 s99, vcc_hi, s9
	global_load_lds_dwordx4 v138, s[98:99]
	s_add_i32 m0, s36, 0x2000
	s_nop 0
	s_add_u32 s98, vcc_lo, s10
	s_addc_u32 s99, vcc_hi, s11
	global_load_lds_dwordx4 v138, s[98:99]
	s_mov_b32 m0, s77
	s_nop 0
	global_load_lds_dwordx4 v136, s[80:81]
	s_mov_b32 m0, s97
	s_nop 0
	s_add_u32 s98, s80, s6
	s_addc_u32 s99, s81, s7
	global_load_lds_dwordx4 v136, s[98:99]
	s_waitcnt vmcnt(8)
	s_waitcnt lgkmcnt(0)
	s_barrier
	s_setprio 1
	s_waitcnt lgkmcnt(0)
	v_mfma_i32_16x16x64_i8 v[20:23], v[128:131], v[184:187], v[20:23]
	v_mfma_i32_16x16x64_i8 v[20:23], v[132:135], v[188:191], v[20:23]
	v_mfma_i32_16x16x64_i8 v[40:43], v[146:149], v[184:187], v[40:43]
	v_mfma_i32_16x16x64_i8 v[40:43], v[164:167], v[188:191], v[40:43]
	v_mfma_i32_16x16x64_i8 v[16:19], v[128:131], v[192:195], v[16:19]
	v_mfma_i32_16x16x64_i8 v[16:19], v[132:135], v[196:199], v[16:19]
	v_mfma_i32_16x16x64_i8 v[36:39], v[146:149], v[192:195], v[36:39]
	v_mfma_i32_16x16x64_i8 v[36:39], v[164:167], v[196:199], v[36:39]
	v_mfma_i32_16x16x64_i8 v[24:27], v[128:131], v[200:203], v[24:27]
	v_mfma_i32_16x16x64_i8 v[24:27], v[132:135], v[204:207], v[24:27]
	v_mfma_i32_16x16x64_i8 v[32:35], v[146:149], v[200:203], v[32:35]
	v_mfma_i32_16x16x64_i8 v[32:35], v[164:167], v[204:207], v[32:35]
	v_mfma_i32_16x16x64_i8 v[28:31], v[128:131], v[208:211], v[28:31]
	v_mfma_i32_16x16x64_i8 v[28:31], v[132:135], v[212:215], v[28:31]
	v_mfma_i32_16x16x64_i8 v[60:63], v[146:149], v[208:211], v[60:63]
	v_mfma_i32_16x16x64_i8 v[60:63], v[164:167], v[212:215], v[60:63]
	s_setprio 0
	s_setprio 1
	v_mfma_i32_16x16x64_i8 v[72:75], v[168:171], v[184:187], v[72:75]
	v_mfma_i32_16x16x64_i8 v[72:75], v[172:175], v[188:191], v[72:75]
	v_mfma_i32_16x16x64_i8 v[104:107], v[176:179], v[184:187], v[104:107]
	v_mfma_i32_16x16x64_i8 v[104:107], v[180:183], v[188:191], v[104:107]
	v_mfma_i32_16x16x64_i8 v[68:71], v[168:171], v[192:195], v[68:71]
	v_mfma_i32_16x16x64_i8 v[68:71], v[172:175], v[196:199], v[68:71]
	v_mfma_i32_16x16x64_i8 v[100:103], v[176:179], v[192:195], v[100:103]
	v_mfma_i32_16x16x64_i8 v[100:103], v[180:183], v[196:199], v[100:103]
	s_setprio 2
	s_barrier
	v_mfma_i32_16x16x64_i8 v[64:67], v[168:171], v[200:203], v[64:67]
	v_mfma_i32_16x16x64_i8 v[64:67], v[172:175], v[204:207], v[64:67]
	v_mfma_i32_16x16x64_i8 v[96:99], v[176:179], v[200:203], v[96:99]
	v_mfma_i32_16x16x64_i8 v[96:99], v[180:183], v[204:207], v[96:99]
	v_mfma_i32_16x16x64_i8 v[92:95], v[168:171], v[208:211], v[92:95]
	v_mfma_i32_16x16x64_i8 v[92:95], v[172:175], v[212:215], v[92:95]
	v_mfma_i32_16x16x64_i8 v[124:127], v[176:179], v[208:211], v[124:127]
	v_mfma_i32_16x16x64_i8 v[124:127], v[180:183], v[212:215], v[124:127]
	s_setprio 0
	s_add_i32 s36, 0, 0x18000
	v_add_u32_e32 v152, s36, v153
	s_add_i32 s37, 0, 0x1c000
	ds_read_b128 v[128:131], v152
	ds_read_b128 v[132:135], v152 offset:1024
	ds_read_b128 v[146:149], v152 offset:2048
	ds_read_b128 v[164:167], v152 offset:3072
	v_add_u32_e32 v152, s37, v153
	ds_read_b128 v[168:171], v152
	ds_read_b128 v[172:175], v152 offset:1024
	ds_read_b128 v[176:179], v152 offset:2048
	ds_read_b128 v[180:183], v152 offset:3072
	s_mov_b32 m0, s33
	ds_read_b128 v[184:187], v161 offset:32768
	ds_read_b128 v[188:191], v161 offset:33792
	ds_read_b128 v[192:195], v161 offset:34816
	ds_read_b128 v[196:199], v161 offset:35840
	ds_read_b128 v[200:203], v161 offset:36864
	ds_read_b128 v[204:207], v161 offset:37888
	ds_read_b128 v[208:211], v161 offset:38912
	ds_read_b128 v[212:215], v161 offset:39936
	s_add_u32 s98, s80, s8
	s_addc_u32 s99, s81, s9
	global_load_lds_dwordx4 v136, s[98:99]
	s_mov_b32 m0, s93
	s_nop 0
	s_add_u32 s98, s80, s10
	s_addc_u32 s99, s81, s11
	global_load_lds_dwordx4 v136, s[98:99]
	s_waitcnt vmcnt(8)
	s_waitcnt lgkmcnt(0)
	s_barrier
	s_setprio 1
	s_waitcnt lgkmcnt(0)
	v_mfma_i32_16x16x64_i8 v[0:3], v[128:131], v[184:187], v[0:3]
	v_mfma_i32_16x16x64_i8 v[0:3], v[132:135], v[188:191], v[0:3]
	v_mfma_i32_16x16x64_i8 v[56:59], v[146:149], v[184:187], v[56:59]
	v_mfma_i32_16x16x64_i8 v[56:59], v[164:167], v[188:191], v[56:59]
	v_mfma_i32_16x16x64_i8 v[4:7], v[128:131], v[192:195], v[4:7]
	v_mfma_i32_16x16x64_i8 v[4:7], v[132:135], v[196:199], v[4:7]
	v_mfma_i32_16x16x64_i8 v[52:55], v[146:149], v[192:195], v[52:55]
	v_mfma_i32_16x16x64_i8 v[52:55], v[164:167], v[196:199], v[52:55]
	v_mfma_i32_16x16x64_i8 v[12:15], v[128:131], v[200:203], v[12:15]
	v_mfma_i32_16x16x64_i8 v[12:15], v[132:135], v[204:207], v[12:15]
	v_mfma_i32_16x16x64_i8 v[48:51], v[146:149], v[200:203], v[48:51]
	v_mfma_i32_16x16x64_i8 v[48:51], v[164:167], v[204:207], v[48:51]
	v_mfma_i32_16x16x64_i8 v[8:11], v[128:131], v[208:211], v[8:11]
	v_mfma_i32_16x16x64_i8 v[8:11], v[132:135], v[212:215], v[8:11]
	v_mfma_i32_16x16x64_i8 v[44:47], v[146:149], v[208:211], v[44:47]
	v_mfma_i32_16x16x64_i8 v[44:47], v[164:167], v[212:215], v[44:47]
	s_setprio 0
	s_setprio 1
	v_mfma_i32_16x16x64_i8 v[88:91], v[168:171], v[184:187], v[88:91]
	v_mfma_i32_16x16x64_i8 v[88:91], v[172:175], v[188:191], v[88:91]
	v_mfma_i32_16x16x64_i8 v[120:123], v[176:179], v[184:187], v[120:123]
	v_mfma_i32_16x16x64_i8 v[120:123], v[180:183], v[188:191], v[120:123]
	v_mfma_i32_16x16x64_i8 v[84:87], v[168:171], v[192:195], v[84:87]
	v_mfma_i32_16x16x64_i8 v[84:87], v[172:175], v[196:199], v[84:87]
	v_mfma_i32_16x16x64_i8 v[116:119], v[176:179], v[192:195], v[116:119]
	v_mfma_i32_16x16x64_i8 v[116:119], v[180:183], v[196:199], v[116:119]
	s_setprio 2
	s_barrier
	v_mfma_i32_16x16x64_i8 v[80:83], v[168:171], v[200:203], v[80:83]
	v_mfma_i32_16x16x64_i8 v[80:83], v[172:175], v[204:207], v[80:83]
	v_mfma_i32_16x16x64_i8 v[112:115], v[176:179], v[200:203], v[112:115]
	v_mfma_i32_16x16x64_i8 v[112:115], v[180:183], v[204:207], v[112:115]
	v_mfma_i32_16x16x64_i8 v[76:79], v[168:171], v[208:211], v[76:79]
	v_mfma_i32_16x16x64_i8 v[76:79], v[172:175], v[212:215], v[76:79]
	v_mfma_i32_16x16x64_i8 v[108:111], v[176:179], v[208:211], v[108:111]
	v_mfma_i32_16x16x64_i8 v[108:111], v[180:183], v[212:215], v[108:111]
	s_setprio 0
	s_add_i32 s36, s36, s63
	s_mov_b32 m0, s36
	ds_read_b128 v[184:187], v161 offset:49152
	ds_read_b128 v[188:191], v161 offset:50176
	ds_read_b128 v[192:195], v161 offset:51200
	ds_read_b128 v[196:199], v161 offset:52224
	ds_read_b128 v[200:203], v161 offset:53248
	ds_read_b128 v[204:207], v161 offset:54272
	ds_read_b128 v[208:211], v161 offset:55296
	ds_read_b128 v[212:215], v161 offset:56320
	s_add_u32 s98, vcc_lo, s46
	s_addc_u32 s99, vcc_hi, s47
	global_load_lds_dwordx4 v138, s[98:99]
	s_add_i32 m0, s36, 0x2000
	s_add_i32 s36, s37, s63
	s_add_u32 s98, vcc_lo, s48
	s_addc_u32 s99, vcc_hi, s49
	global_load_lds_dwordx4 v138, s[98:99]
	s_mov_b32 m0, s36
	s_add_u32 s98, vcc_lo, s54
	s_addc_u32 s99, vcc_hi, s55
	global_load_lds_dwordx4 v138, s[98:99]
	s_add_i32 m0, s36, 0x2000
	s_nop 0
	s_add_u32 s98, vcc_lo, s56
	s_addc_u32 s99, vcc_hi, s57
	global_load_lds_dwordx4 v138, s[98:99]
	s_mov_b32 m0, s95
	s_nop 0
	s_add_u32 s98, s80, s46
	s_addc_u32 s99, s81, s47
	global_load_lds_dwordx4 v136, s[98:99]
	s_mov_b32 m0, s82
	s_nop 0
	s_add_u32 s98, s80, s48
	s_addc_u32 s99, s81, s49
	global_load_lds_dwordx4 v136, s[98:99]
	s_waitcnt vmcnt(8)
	s_waitcnt lgkmcnt(0)
	s_barrier
	s_setprio 1
	s_waitcnt lgkmcnt(0)
	v_mfma_i32_16x16x64_i8 v[20:23], v[128:131], v[184:187], v[20:23]
	v_mfma_i32_16x16x64_i8 v[20:23], v[132:135], v[188:191], v[20:23]
	v_mfma_i32_16x16x64_i8 v[40:43], v[146:149], v[184:187], v[40:43]
	v_mfma_i32_16x16x64_i8 v[40:43], v[164:167], v[188:191], v[40:43]
	v_mfma_i32_16x16x64_i8 v[16:19], v[128:131], v[192:195], v[16:19]
	v_mfma_i32_16x16x64_i8 v[16:19], v[132:135], v[196:199], v[16:19]
	v_mfma_i32_16x16x64_i8 v[36:39], v[146:149], v[192:195], v[36:39]
	v_mfma_i32_16x16x64_i8 v[36:39], v[164:167], v[196:199], v[36:39]
	v_mfma_i32_16x16x64_i8 v[24:27], v[128:131], v[200:203], v[24:27]
	v_mfma_i32_16x16x64_i8 v[24:27], v[132:135], v[204:207], v[24:27]
	v_mfma_i32_16x16x64_i8 v[32:35], v[146:149], v[200:203], v[32:35]
	v_mfma_i32_16x16x64_i8 v[32:35], v[164:167], v[204:207], v[32:35]
	v_mfma_i32_16x16x64_i8 v[28:31], v[128:131], v[208:211], v[28:31]
	v_mfma_i32_16x16x64_i8 v[28:31], v[132:135], v[212:215], v[28:31]
	v_mfma_i32_16x16x64_i8 v[60:63], v[146:149], v[208:211], v[60:63]
	v_mfma_i32_16x16x64_i8 v[60:63], v[164:167], v[212:215], v[60:63]
	s_setprio 0
	s_setprio 1
	v_mfma_i32_16x16x64_i8 v[72:75], v[168:171], v[184:187], v[72:75]
	v_mfma_i32_16x16x64_i8 v[72:75], v[172:175], v[188:191], v[72:75]
	v_mfma_i32_16x16x64_i8 v[104:107], v[176:179], v[184:187], v[104:107]
	v_mfma_i32_16x16x64_i8 v[104:107], v[180:183], v[188:191], v[104:107]
	v_mfma_i32_16x16x64_i8 v[68:71], v[168:171], v[192:195], v[68:71]
	v_mfma_i32_16x16x64_i8 v[68:71], v[172:175], v[196:199], v[68:71]
	v_mfma_i32_16x16x64_i8 v[100:103], v[176:179], v[192:195], v[100:103]
	v_mfma_i32_16x16x64_i8 v[100:103], v[180:183], v[196:199], v[100:103]
	s_setprio 2
	s_barrier
	v_mfma_i32_16x16x64_i8 v[64:67], v[168:171], v[200:203], v[64:67]
	v_mfma_i32_16x16x64_i8 v[64:67], v[172:175], v[204:207], v[64:67]
	v_mfma_i32_16x16x64_i8 v[96:99], v[176:179], v[200:203], v[96:99]
	v_mfma_i32_16x16x64_i8 v[96:99], v[180:183], v[204:207], v[96:99]
	v_mfma_i32_16x16x64_i8 v[92:95], v[168:171], v[208:211], v[92:95]
	v_mfma_i32_16x16x64_i8 v[92:95], v[172:175], v[212:215], v[92:95]
	v_mfma_i32_16x16x64_i8 v[124:127], v[176:179], v[208:211], v[124:127]
	v_mfma_i32_16x16x64_i8 v[124:127], v[180:183], v[212:215], v[124:127]
	s_setprio 0
	s_add_i32 s78, s78, 2
	s_add_u32 s24, s24, 0x100
	s_addc_u32 s45, s45, 0
	s_add_u32 s22, s22, 0x100
	s_addc_u32 s23, s23, 0
	s_cmp_gt_u32 s78, 29
	s_cbranch_scc0 .LBB0_225
	v_readlane_b32 s14, v250, 9
	v_readlane_b32 s15, v250, 10
	s_and_b64 vcc, exec, s[14:15]
	s_cbranch_vccz .LBB0_228
	s_barrier

.LBB0_298:
	ds_read_b128 v[128:131], v153
	ds_read_b128 v[132:135], v153 offset:1024
	ds_read_b128 v[146:149], v153 offset:2048
	ds_read_b128 v[158:161], v153 offset:3072
	ds_read_b128 v[162:165], v154
	ds_read_b128 v[166:169], v154 offset:1024
	ds_read_b128 v[170:173], v154 offset:2048
	ds_read_b128 v[174:177], v154 offset:3072
	s_add_u32 s36, s78, 0xfff00080
	s_addc_u32 s37, s79, -1
	s_cmp_eq_u32 s81, 60
	s_cselect_b32 s97, s5, s37
	s_cselect_b32 s96, s14, s36
	s_cselect_b32 vcc_hi, s20, s80
	s_cselect_b32 vcc_lo, s21, s22
	s_add_i32 m0, s33, 0xc000
	ds_read_b128 v[178:181], v155
	ds_read_b128 v[182:185], v155 offset:1024
	ds_read_b128 v[186:189], v155 offset:2048
	ds_read_b128 v[190:193], v155 offset:3072
	ds_read_b128 v[194:197], v155 offset:4096
	ds_read_b128 v[198:201], v155 offset:5120
	ds_read_b128 v[202:205], v155 offset:6144
	ds_read_b128 v[206:209], v155 offset:7168
	global_load_lds_dwordx4 v140, s[78:79]
	s_add_i32 m0, s33, 0xe000
	s_nop 0
	s_add_u32 s98, s78, s0
	s_addc_u32 s99, s79, s1
	global_load_lds_dwordx4 v140, s[98:99]
	s_waitcnt vmcnt(8)
	s_waitcnt lgkmcnt(0)
	s_barrier
	s_setprio 1
	s_waitcnt lgkmcnt(0)
	v_mfma_f32_16x16x32_bf16 v[124:127], v[128:131], v[178:181], v[124:127]
	v_mfma_f32_16x16x32_bf16 v[124:127], v[132:135], v[182:185], v[124:127]
	v_mfma_f32_16x16x32_bf16 v[120:123], v[146:149], v[178:181], v[120:123]
	v_mfma_f32_16x16x32_bf16 v[120:123], v[158:161], v[182:185], v[120:123]
	v_mfma_f32_16x16x32_bf16 v[112:115], v[128:131], v[186:189], v[112:115]
	v_mfma_f32_16x16x32_bf16 v[112:115], v[132:135], v[190:193], v[112:115]
	v_mfma_f32_16x16x32_bf16 v[108:111], v[146:149], v[186:189], v[108:111]
	v_mfma_f32_16x16x32_bf16 v[108:111], v[158:161], v[190:193], v[108:111]
	v_mfma_f32_16x16x32_bf16 v[100:103], v[128:131], v[194:197], v[100:103]
	v_mfma_f32_16x16x32_bf16 v[100:103], v[132:135], v[198:201], v[100:103]
	v_mfma_f32_16x16x32_bf16 v[92:95], v[146:149], v[194:197], v[92:95]
	v_mfma_f32_16x16x32_bf16 v[92:95], v[158:161], v[198:201], v[92:95]
	v_mfma_f32_16x16x32_bf16 v[84:87], v[128:131], v[202:205], v[84:87]
	v_mfma_f32_16x16x32_bf16 v[84:87], v[132:135], v[206:209], v[84:87]
	v_mfma_f32_16x16x32_bf16 v[76:79], v[146:149], v[202:205], v[76:79]
	v_mfma_f32_16x16x32_bf16 v[76:79], v[158:161], v[206:209], v[76:79]
	s_setprio 0
	s_setprio 1
	v_mfma_f32_16x16x32_bf16 v[116:119], v[162:165], v[178:181], v[116:119]
	v_mfma_f32_16x16x32_bf16 v[116:119], v[166:169], v[182:185], v[116:119]
	v_mfma_f32_16x16x32_bf16 v[104:107], v[170:173], v[178:181], v[104:107]
	v_mfma_f32_16x16x32_bf16 v[104:107], v[174:177], v[182:185], v[104:107]
	v_mfma_f32_16x16x32_bf16 v[96:99], v[162:165], v[186:189], v[96:99]
	v_mfma_f32_16x16x32_bf16 v[96:99], v[166:169], v[190:193], v[96:99]
	v_mfma_f32_16x16x32_bf16 v[88:91], v[170:173], v[186:189], v[88:91]
	v_mfma_f32_16x16x32_bf16 v[88:91], v[174:177], v[190:193], v[88:91]
	s_setprio 2
	s_barrier
	v_mfma_f32_16x16x32_bf16 v[80:83], v[162:165], v[194:197], v[80:83]
	v_mfma_f32_16x16x32_bf16 v[80:83], v[166:169], v[198:201], v[80:83]
	v_mfma_f32_16x16x32_bf16 v[72:75], v[170:173], v[194:197], v[72:75]
	v_mfma_f32_16x16x32_bf16 v[72:75], v[174:177], v[198:201], v[72:75]
	v_mfma_f32_16x16x32_bf16 v[68:71], v[162:165], v[202:205], v[68:71]
	v_mfma_f32_16x16x32_bf16 v[68:71], v[166:169], v[206:209], v[68:71]
	v_mfma_f32_16x16x32_bf16 v[64:67], v[170:173], v[202:205], v[64:67]
	v_mfma_f32_16x16x32_bf16 v[64:67], v[174:177], v[206:209], v[64:67]
	s_setprio 0
	s_add_i32 s36, s82, s63
	s_mov_b32 m0, s36
	ds_read_b128 v[178:181], v155 offset:16384
	ds_read_b128 v[182:185], v155 offset:17408
	ds_read_b128 v[186:189], v155 offset:18432
	ds_read_b128 v[190:193], v155 offset:19456
	ds_read_b128 v[194:197], v155 offset:20480
	ds_read_b128 v[198:201], v155 offset:21504
	ds_read_b128 v[202:205], v155 offset:22528
	ds_read_b128 v[206:209], v155 offset:23552
	global_load_lds_dwordx4 v138, vcc
	s_add_i32 m0, s36, 0x2000
	s_add_i32 s36, s83, s63
	s_add_u32 s98, vcc_lo, s0
	s_addc_u32 s99, vcc_hi, s1
	global_load_lds_dwordx4 v138, s[98:99]
	s_mov_b32 m0, s36
	s_nop 0
	s_add_u32 s98, vcc_lo, s6
	s_addc_u32 s99, vcc_hi, s7
	global_load_lds_dwordx4 v138, s[98:99]
	s_add_i32 m0, s36, 0x2000
	s_nop 0
	s_add_u32 s98, vcc_lo, s8
	s_addc_u32 s99, vcc_hi, s9
	global_load_lds_dwordx4 v138, s[98:99]
	s_mov_b32 m0, s33
	s_nop 0
	global_load_lds_dwordx4 v136, s[96:97]
	s_mov_b32 m0, s55
	s_nop 0
	s_add_u32 s98, s96, s0
	s_addc_u32 s99, s97, s1
	global_load_lds_dwordx4 v136, s[98:99]
	s_waitcnt vmcnt(8)
	s_waitcnt lgkmcnt(0)
	s_barrier
	s_setprio 1
	s_waitcnt lgkmcnt(0)
	v_mfma_f32_16x16x32_bf16 v[60:63], v[128:131], v[178:181], v[60:63]
	v_mfma_f32_16x16x32_bf16 v[60:63], v[132:135], v[182:185], v[60:63]
	v_mfma_f32_16x16x32_bf16 v[56:59], v[146:149], v[178:181], v[56:59]
	v_mfma_f32_16x16x32_bf16 v[56:59], v[158:161], v[182:185], v[56:59]
	v_mfma_f32_16x16x32_bf16 v[52:55], v[128:131], v[186:189], v[52:55]
	v_mfma_f32_16x16x32_bf16 v[52:55], v[132:135], v[190:193], v[52:55]
	v_mfma_f32_16x16x32_bf16 v[44:47], v[146:149], v[186:189], v[44:47]
	v_mfma_f32_16x16x32_bf16 v[44:47], v[158:161], v[190:193], v[44:47]
	v_mfma_f32_16x16x32_bf16 v[36:39], v[128:131], v[194:197], v[36:39]
	v_mfma_f32_16x16x32_bf16 v[36:39], v[132:135], v[198:201], v[36:39]
	v_mfma_f32_16x16x32_bf16 v[28:31], v[146:149], v[194:197], v[28:31]
	v_mfma_f32_16x16x32_bf16 v[28:31], v[158:161], v[198:201], v[28:31]
	v_mfma_f32_16x16x32_bf16 v[20:23], v[128:131], v[202:205], v[20:23]
	v_mfma_f32_16x16x32_bf16 v[20:23], v[132:135], v[206:209], v[20:23]
	v_mfma_f32_16x16x32_bf16 v[12:15], v[146:149], v[202:205], v[12:15]
	v_mfma_f32_16x16x32_bf16 v[12:15], v[158:161], v[206:209], v[12:15]
	s_setprio 0
	s_setprio 1
	v_mfma_f32_16x16x32_bf16 v[48:51], v[162:165], v[178:181], v[48:51]
	v_mfma_f32_16x16x32_bf16 v[48:51], v[166:169], v[182:185], v[48:51]
	v_mfma_f32_16x16x32_bf16 v[40:43], v[170:173], v[178:181], v[40:43]
	v_mfma_f32_16x16x32_bf16 v[40:43], v[174:177], v[182:185], v[40:43]
	v_mfma_f32_16x16x32_bf16 v[32:35], v[162:165], v[186:189], v[32:35]
	v_mfma_f32_16x16x32_bf16 v[32:35], v[166:169], v[190:193], v[32:35]
	v_mfma_f32_16x16x32_bf16 v[24:27], v[170:173], v[186:189], v[24:27]
	v_mfma_f32_16x16x32_bf16 v[24:27], v[174:177], v[190:193], v[24:27]
	s_setprio 2
	s_barrier
	v_mfma_f32_16x16x32_bf16 v[16:19], v[162:165], v[194:197], v[16:19]
	v_mfma_f32_16x16x32_bf16 v[16:19], v[166:169], v[198:201], v[16:19]
	v_mfma_f32_16x16x32_bf16 v[8:11], v[170:173], v[194:197], v[8:11]
	v_mfma_f32_16x16x32_bf16 v[8:11], v[174:177], v[198:201], v[8:11]
	v_mfma_f32_16x16x32_bf16 v[4:7], v[162:165], v[202:205], v[4:7]
	v_mfma_f32_16x16x32_bf16 v[4:7], v[166:169], v[206:209], v[4:7]
	v_mfma_f32_16x16x32_bf16 v[0:3], v[170:173], v[202:205], v[0:3]
	v_mfma_f32_16x16x32_bf16 v[0:3], v[174:177], v[206:209], v[0:3]
	s_setprio 0
	s_add_i32 s36, 0, 0x18000
	v_add_u32_e32 v157, s36, v152
	s_add_i32 s37, 0, 0x1c000
	ds_read_b128 v[128:131], v157
	ds_read_b128 v[132:135], v157 offset:1024
	ds_read_b128 v[146:149], v157 offset:2048
	ds_read_b128 v[158:161], v157 offset:3072
	v_add_u32_e32 v157, s37, v152
	ds_read_b128 v[162:165], v157
	ds_read_b128 v[166:169], v157 offset:1024
	ds_read_b128 v[170:173], v157 offset:2048
	ds_read_b128 v[174:177], v157 offset:3072
	s_mov_b32 m0, s57
	ds_read_b128 v[178:181], v155 offset:32768
	ds_read_b128 v[182:185], v155 offset:33792
	ds_read_b128 v[186:189], v155 offset:34816
	ds_read_b128 v[190:193], v155 offset:35840
	ds_read_b128 v[194:197], v155 offset:36864
	ds_read_b128 v[198:201], v155 offset:37888
	ds_read_b128 v[202:205], v155 offset:38912
	ds_read_b128 v[206:209], v155 offset:39936
	s_add_u32 s98, s96, s6
	s_addc_u32 s99, s97, s7
	global_load_lds_dwordx4 v136, s[98:99]
	s_mov_b32 m0, s59
	s_nop 0
	s_add_u32 s98, s96, s8
	s_addc_u32 s99, s97, s9
	global_load_lds_dwordx4 v136, s[98:99]
	s_waitcnt vmcnt(8)
	s_waitcnt lgkmcnt(0)
	s_barrier
	s_setprio 1
	s_waitcnt lgkmcnt(0)
	v_mfma_f32_16x16x32_bf16 v[124:127], v[128:131], v[178:181], v[124:127]
	v_mfma_f32_16x16x32_bf16 v[124:127], v[132:135], v[182:185], v[124:127]
	v_mfma_f32_16x16x32_bf16 v[120:123], v[146:149], v[178:181], v[120:123]
	v_mfma_f32_16x16x32_bf16 v[120:123], v[158:161], v[182:185], v[120:123]
	v_mfma_f32_16x16x32_bf16 v[112:115], v[128:131], v[186:189], v[112:115]
	v_mfma_f32_16x16x32_bf16 v[112:115], v[132:135], v[190:193], v[112:115]
	v_mfma_f32_16x16x32_bf16 v[108:111], v[146:149], v[186:189], v[108:111]
	v_mfma_f32_16x16x32_bf16 v[108:111], v[158:161], v[190:193], v[108:111]
	v_mfma_f32_16x16x32_bf16 v[100:103], v[128:131], v[194:197], v[100:103]
	v_mfma_f32_16x16x32_bf16 v[100:103], v[132:135], v[198:201], v[100:103]
	v_mfma_f32_16x16x32_bf16 v[92:95], v[146:149], v[194:197], v[92:95]
	v_mfma_f32_16x16x32_bf16 v[92:95], v[158:161], v[198:201], v[92:95]
	v_mfma_f32_16x16x32_bf16 v[84:87], v[128:131], v[202:205], v[84:87]
	v_mfma_f32_16x16x32_bf16 v[84:87], v[132:135], v[206:209], v[84:87]
	v_mfma_f32_16x16x32_bf16 v[76:79], v[146:149], v[202:205], v[76:79]
	v_mfma_f32_16x16x32_bf16 v[76:79], v[158:161], v[206:209], v[76:79]
	s_setprio 0
	s_setprio 1
	v_mfma_f32_16x16x32_bf16 v[116:119], v[162:165], v[178:181], v[116:119]
	v_mfma_f32_16x16x32_bf16 v[116:119], v[166:169], v[182:185], v[116:119]
	v_mfma_f32_16x16x32_bf16 v[104:107], v[170:173], v[178:181], v[104:107]
	v_mfma_f32_16x16x32_bf16 v[104:107], v[174:177], v[182:185], v[104:107]
	v_mfma_f32_16x16x32_bf16 v[96:99], v[162:165], v[186:189], v[96:99]
	v_mfma_f32_16x16x32_bf16 v[96:99], v[166:169], v[190:193], v[96:99]
	v_mfma_f32_16x16x32_bf16 v[88:91], v[170:173], v[186:189], v[88:91]
	v_mfma_f32_16x16x32_bf16 v[88:91], v[174:177], v[190:193], v[88:91]
	s_setprio 2
	s_barrier
	v_mfma_f32_16x16x32_bf16 v[80:83], v[162:165], v[194:197], v[80:83]
	v_mfma_f32_16x16x32_bf16 v[80:83], v[166:169], v[198:201], v[80:83]
	v_mfma_f32_16x16x32_bf16 v[72:75], v[170:173], v[194:197], v[72:75]
	v_mfma_f32_16x16x32_bf16 v[72:75], v[174:177], v[198:201], v[72:75]
	v_mfma_f32_16x16x32_bf16 v[68:71], v[162:165], v[202:205], v[68:71]
	v_mfma_f32_16x16x32_bf16 v[68:71], v[166:169], v[206:209], v[68:71]
	v_mfma_f32_16x16x32_bf16 v[64:67], v[170:173], v[202:205], v[64:67]
	v_mfma_f32_16x16x32_bf16 v[64:67], v[174:177], v[206:209], v[64:67]
	s_setprio 0
	s_add_i32 s36, s36, s63
	s_mov_b32 m0, s36
	ds_read_b128 v[178:181], v155 offset:49152
	ds_read_b128 v[182:185], v155 offset:50176
	ds_read_b128 v[186:189], v155 offset:51200
	ds_read_b128 v[190:193], v155 offset:52224
	ds_read_b128 v[194:197], v155 offset:53248
	ds_read_b128 v[198:201], v155 offset:54272
	ds_read_b128 v[202:205], v155 offset:55296
	ds_read_b128 v[206:209], v155 offset:56320
	s_add_u32 s98, vcc_lo, s24
	s_addc_u32 s99, vcc_hi, s25
	global_load_lds_dwordx4 v138, s[98:99]
	s_add_i32 m0, s36, 0x2000
	s_add_i32 s36, s37, s63
	s_add_u32 s98, vcc_lo, s34
	s_addc_u32 s99, vcc_hi, s35
	global_load_lds_dwordx4 v138, s[98:99]
	s_mov_b32 m0, s36
	s_add_u32 s98, vcc_lo, s12
	s_addc_u32 s99, vcc_hi, s13
	global_load_lds_dwordx4 v138, s[98:99]
	s_add_i32 m0, s36, 0x2000
	s_nop 0
	s_add_u32 s98, vcc_lo, s18
	s_addc_u32 s99, vcc_hi, s19
	global_load_lds_dwordx4 v138, s[98:99]
	s_mov_b32 m0, s68
	s_nop 0
	s_add_u32 s98, s96, s24
	s_addc_u32 s99, s97, s25
	global_load_lds_dwordx4 v136, s[98:99]
	s_mov_b32 m0, s69
	s_nop 0
	s_add_u32 s98, s96, s34
	s_addc_u32 s99, s97, s35
	global_load_lds_dwordx4 v136, s[98:99]
	s_waitcnt vmcnt(8)
	s_waitcnt lgkmcnt(0)
	s_barrier
	s_setprio 1
	s_waitcnt lgkmcnt(0)
	v_mfma_f32_16x16x32_bf16 v[60:63], v[128:131], v[178:181], v[60:63]
	v_mfma_f32_16x16x32_bf16 v[60:63], v[132:135], v[182:185], v[60:63]
	v_mfma_f32_16x16x32_bf16 v[56:59], v[146:149], v[178:181], v[56:59]
	v_mfma_f32_16x16x32_bf16 v[56:59], v[158:161], v[182:185], v[56:59]
	v_mfma_f32_16x16x32_bf16 v[52:55], v[128:131], v[186:189], v[52:55]
	v_mfma_f32_16x16x32_bf16 v[52:55], v[132:135], v[190:193], v[52:55]
	v_mfma_f32_16x16x32_bf16 v[44:47], v[146:149], v[186:189], v[44:47]
	v_mfma_f32_16x16x32_bf16 v[44:47], v[158:161], v[190:193], v[44:47]
	v_mfma_f32_16x16x32_bf16 v[36:39], v[128:131], v[194:197], v[36:39]
	v_mfma_f32_16x16x32_bf16 v[36:39], v[132:135], v[198:201], v[36:39]
	v_mfma_f32_16x16x32_bf16 v[28:31], v[146:149], v[194:197], v[28:31]
	v_mfma_f32_16x16x32_bf16 v[28:31], v[158:161], v[198:201], v[28:31]
	v_mfma_f32_16x16x32_bf16 v[20:23], v[128:131], v[202:205], v[20:23]
	v_mfma_f32_16x16x32_bf16 v[20:23], v[132:135], v[206:209], v[20:23]
	v_mfma_f32_16x16x32_bf16 v[12:15], v[146:149], v[202:205], v[12:15]
	v_mfma_f32_16x16x32_bf16 v[12:15], v[158:161], v[206:209], v[12:15]
	s_setprio 0
	s_setprio 1
	v_mfma_f32_16x16x32_bf16 v[48:51], v[162:165], v[178:181], v[48:51]
	v_mfma_f32_16x16x32_bf16 v[48:51], v[166:169], v[182:185], v[48:51]
	v_mfma_f32_16x16x32_bf16 v[40:43], v[170:173], v[178:181], v[40:43]
	v_mfma_f32_16x16x32_bf16 v[40:43], v[174:177], v[182:185], v[40:43]
	v_mfma_f32_16x16x32_bf16 v[32:35], v[162:165], v[186:189], v[32:35]
	v_mfma_f32_16x16x32_bf16 v[32:35], v[166:169], v[190:193], v[32:35]
	v_mfma_f32_16x16x32_bf16 v[24:27], v[170:173], v[186:189], v[24:27]
	v_mfma_f32_16x16x32_bf16 v[24:27], v[174:177], v[190:193], v[24:27]
	s_setprio 2
	s_barrier
	v_mfma_f32_16x16x32_bf16 v[16:19], v[162:165], v[194:197], v[16:19]
	v_mfma_f32_16x16x32_bf16 v[16:19], v[166:169], v[198:201], v[16:19]
	v_mfma_f32_16x16x32_bf16 v[8:11], v[170:173], v[194:197], v[8:11]
	v_mfma_f32_16x16x32_bf16 v[8:11], v[174:177], v[198:201], v[8:11]
	v_mfma_f32_16x16x32_bf16 v[4:7], v[162:165], v[202:205], v[4:7]
	v_mfma_f32_16x16x32_bf16 v[4:7], v[166:169], v[206:209], v[4:7]
	v_mfma_f32_16x16x32_bf16 v[0:3], v[170:173], v[202:205], v[0:3]
	v_mfma_f32_16x16x32_bf16 v[0:3], v[174:177], v[206:209], v[0:3]
	s_setprio 0
	s_add_i32 s81, s81, 2
	s_add_u32 s22, s22, 0x100
	s_addc_u32 s80, s80, 0
	s_add_u32 s78, s78, 0x100
	s_addc_u32 s79, s79, 0
	s_cmp_gt_u32 s81, 61
	s_cbranch_scc0 .LBB0_298
	s_and_b64 vcc, exec, s[26:27]
	s_cbranch_vccz .LBB0_301
	s_barrier

.LBB0_627:
	ds_read_b128 v[128:131], v151
	ds_read_b128 v[142:145], v151 offset:1024
	ds_read_b128 v[146:149], v151 offset:2048
	ds_read_b128 v[154:157], v151 offset:3072
	ds_read_b128 v[158:161], v152
	ds_read_b128 v[162:165], v152 offset:1024
	ds_read_b128 v[166:169], v152 offset:2048
	ds_read_b128 v[170:173], v152 offset:3072
	s_add_u32 s50, s60, 0xfff00080
	s_addc_u32 s51, s61, -1
	s_cmp_eq_u32 s62, 60
	s_cselect_b32 s77, s5, s51
	s_cselect_b32 s76, s49, s50
	s_cselect_b32 s79, s47, s75
	s_cselect_b32 s78, s59, s74
	s_add_i32 m0, s20, 0xc000
	ds_read_b128 v[174:177], v153
	ds_read_b128 v[178:181], v153 offset:1024
	ds_read_b128 v[182:185], v153 offset:2048
	ds_read_b128 v[186:189], v153 offset:3072
	ds_read_b128 v[190:193], v153 offset:4096
	ds_read_b128 v[194:197], v153 offset:5120
	ds_read_b128 v[198:201], v153 offset:6144
	ds_read_b128 v[202:205], v153 offset:7168
	global_load_lds_dwordx4 v136, s[60:61]
	s_add_i32 m0, s20, 0xe000
	s_nop 0
	s_add_u32 s98, s60, s6
	s_addc_u32 s99, s61, s7
	global_load_lds_dwordx4 v136, s[98:99]
	s_waitcnt vmcnt(8)
	s_waitcnt lgkmcnt(0)
	s_barrier
	s_setprio 1
	s_waitcnt lgkmcnt(0)
	v_mfma_f32_16x16x32_bf16 v[124:127], v[128:131], v[174:177], v[124:127]
	v_mfma_f32_16x16x32_bf16 v[124:127], v[142:145], v[178:181], v[124:127]
	v_mfma_f32_16x16x32_bf16 v[120:123], v[146:149], v[174:177], v[120:123]
	v_mfma_f32_16x16x32_bf16 v[120:123], v[154:157], v[178:181], v[120:123]
	v_mfma_f32_16x16x32_bf16 v[116:119], v[128:131], v[182:185], v[116:119]
	v_mfma_f32_16x16x32_bf16 v[116:119], v[142:145], v[186:189], v[116:119]
	v_mfma_f32_16x16x32_bf16 v[112:115], v[146:149], v[182:185], v[112:115]
	v_mfma_f32_16x16x32_bf16 v[112:115], v[154:157], v[186:189], v[112:115]
	v_mfma_f32_16x16x32_bf16 v[108:111], v[128:131], v[190:193], v[108:111]
	v_mfma_f32_16x16x32_bf16 v[108:111], v[142:145], v[194:197], v[108:111]
	v_mfma_f32_16x16x32_bf16 v[104:107], v[146:149], v[190:193], v[104:107]
	v_mfma_f32_16x16x32_bf16 v[104:107], v[154:157], v[194:197], v[104:107]
	v_mfma_f32_16x16x32_bf16 v[100:103], v[128:131], v[198:201], v[100:103]
	v_mfma_f32_16x16x32_bf16 v[100:103], v[142:145], v[202:205], v[100:103]
	v_mfma_f32_16x16x32_bf16 v[96:99], v[146:149], v[198:201], v[96:99]
	v_mfma_f32_16x16x32_bf16 v[96:99], v[154:157], v[202:205], v[96:99]
	s_setprio 0
	s_setprio 1
	v_mfma_f32_16x16x32_bf16 v[92:95], v[158:161], v[174:177], v[92:95]
	v_mfma_f32_16x16x32_bf16 v[92:95], v[162:165], v[178:181], v[92:95]
	v_mfma_f32_16x16x32_bf16 v[88:91], v[166:169], v[174:177], v[88:91]
	v_mfma_f32_16x16x32_bf16 v[88:91], v[170:173], v[178:181], v[88:91]
	v_mfma_f32_16x16x32_bf16 v[84:87], v[158:161], v[182:185], v[84:87]
	v_mfma_f32_16x16x32_bf16 v[84:87], v[162:165], v[186:189], v[84:87]
	v_mfma_f32_16x16x32_bf16 v[80:83], v[166:169], v[182:185], v[80:83]
	v_mfma_f32_16x16x32_bf16 v[80:83], v[170:173], v[186:189], v[80:83]
	s_setprio 2
	s_barrier
	v_mfma_f32_16x16x32_bf16 v[76:79], v[158:161], v[190:193], v[76:79]
	v_mfma_f32_16x16x32_bf16 v[76:79], v[162:165], v[194:197], v[76:79]
	v_mfma_f32_16x16x32_bf16 v[72:75], v[166:169], v[190:193], v[72:75]
	v_mfma_f32_16x16x32_bf16 v[72:75], v[170:173], v[194:197], v[72:75]
	v_mfma_f32_16x16x32_bf16 v[68:71], v[158:161], v[198:201], v[68:71]
	v_mfma_f32_16x16x32_bf16 v[68:71], v[162:165], v[202:205], v[68:71]
	v_mfma_f32_16x16x32_bf16 v[64:67], v[166:169], v[198:201], v[64:67]
	v_mfma_f32_16x16x32_bf16 v[64:67], v[170:173], v[202:205], v[64:67]
	s_setprio 0
	s_add_i32 s50, s72, s14
	s_mov_b32 m0, s50
	ds_read_b128 v[174:177], v153 offset:16384
	ds_read_b128 v[178:181], v153 offset:17408
	ds_read_b128 v[182:185], v153 offset:18432
	ds_read_b128 v[186:189], v153 offset:19456
	ds_read_b128 v[190:193], v153 offset:20480
	ds_read_b128 v[194:197], v153 offset:21504
	ds_read_b128 v[198:201], v153 offset:22528
	ds_read_b128 v[202:205], v153 offset:23552
	global_load_lds_dwordx4 v134, s[78:79]
	s_add_i32 m0, s50, 0x2000
	s_add_i32 s50, s73, s14
	s_add_u32 s98, s78, s6
	s_addc_u32 s99, s79, s7
	global_load_lds_dwordx4 v134, s[98:99]
	s_mov_b32 m0, s50
	s_nop 0
	s_add_u32 s98, s78, s8
	s_addc_u32 s99, s79, s9
	global_load_lds_dwordx4 v134, s[98:99]
	s_add_i32 m0, s50, 0x2000
	s_nop 0
	s_add_u32 s98, s78, s10
	s_addc_u32 s99, s79, s11
	global_load_lds_dwordx4 v134, s[98:99]
	s_mov_b32 m0, s20
	s_nop 0
	global_load_lds_dwordx4 v132, s[76:77]
	s_mov_b32 m0, s21
	s_nop 0
	s_add_u32 s98, s76, s6
	s_addc_u32 s99, s77, s7
	global_load_lds_dwordx4 v132, s[98:99]
	s_waitcnt vmcnt(8)
	s_waitcnt lgkmcnt(0)
	s_barrier
	s_setprio 1
	s_waitcnt lgkmcnt(0)
	v_mfma_f32_16x16x32_bf16 v[60:63], v[128:131], v[174:177], v[60:63]
	v_mfma_f32_16x16x32_bf16 v[60:63], v[142:145], v[178:181], v[60:63]
	v_mfma_f32_16x16x32_bf16 v[56:59], v[146:149], v[174:177], v[56:59]
	v_mfma_f32_16x16x32_bf16 v[56:59], v[154:157], v[178:181], v[56:59]
	v_mfma_f32_16x16x32_bf16 v[52:55], v[128:131], v[182:185], v[52:55]
	v_mfma_f32_16x16x32_bf16 v[52:55], v[142:145], v[186:189], v[52:55]
	v_mfma_f32_16x16x32_bf16 v[48:51], v[146:149], v[182:185], v[48:51]
	v_mfma_f32_16x16x32_bf16 v[48:51], v[154:157], v[186:189], v[48:51]
	v_mfma_f32_16x16x32_bf16 v[44:47], v[128:131], v[190:193], v[44:47]
	v_mfma_f32_16x16x32_bf16 v[44:47], v[142:145], v[194:197], v[44:47]
	v_mfma_f32_16x16x32_bf16 v[40:43], v[146:149], v[190:193], v[40:43]
	v_mfma_f32_16x16x32_bf16 v[40:43], v[154:157], v[194:197], v[40:43]
	v_mfma_f32_16x16x32_bf16 v[36:39], v[128:131], v[198:201], v[36:39]
	v_mfma_f32_16x16x32_bf16 v[36:39], v[142:145], v[202:205], v[36:39]
	v_mfma_f32_16x16x32_bf16 v[32:35], v[146:149], v[198:201], v[32:35]
	v_mfma_f32_16x16x32_bf16 v[32:35], v[154:157], v[202:205], v[32:35]
	s_setprio 0
	s_setprio 1
	v_mfma_f32_16x16x32_bf16 v[28:31], v[158:161], v[174:177], v[28:31]
	v_mfma_f32_16x16x32_bf16 v[28:31], v[162:165], v[178:181], v[28:31]
	v_mfma_f32_16x16x32_bf16 v[24:27], v[166:169], v[174:177], v[24:27]
	v_mfma_f32_16x16x32_bf16 v[24:27], v[170:173], v[178:181], v[24:27]
	v_mfma_f32_16x16x32_bf16 v[20:23], v[158:161], v[182:185], v[20:23]
	v_mfma_f32_16x16x32_bf16 v[20:23], v[162:165], v[186:189], v[20:23]
	v_mfma_f32_16x16x32_bf16 v[16:19], v[166:169], v[182:185], v[16:19]
	v_mfma_f32_16x16x32_bf16 v[16:19], v[170:173], v[186:189], v[16:19]
	s_setprio 2
	s_barrier
	v_mfma_f32_16x16x32_bf16 v[12:15], v[158:161], v[190:193], v[12:15]
	v_mfma_f32_16x16x32_bf16 v[12:15], v[162:165], v[194:197], v[12:15]
	v_mfma_f32_16x16x32_bf16 v[8:11], v[166:169], v[190:193], v[8:11]
	v_mfma_f32_16x16x32_bf16 v[8:11], v[170:173], v[194:197], v[8:11]
	v_mfma_f32_16x16x32_bf16 v[4:7], v[158:161], v[198:201], v[4:7]
	v_mfma_f32_16x16x32_bf16 v[4:7], v[162:165], v[202:205], v[4:7]
	v_mfma_f32_16x16x32_bf16 v[0:3], v[166:169], v[198:201], v[0:3]
	v_mfma_f32_16x16x32_bf16 v[0:3], v[170:173], v[202:205], v[0:3]
	s_setprio 0
	s_add_i32 s50, 0, 0x18000
	s_add_i32 s51, 0, 0x1c000
	v_add_u32_e32 v154, s50, v150
	v_add_u32_e32 v170, s51, v150
	ds_read_b128 v[128:131], v154
	ds_read_b128 v[142:145], v154 offset:1024
	ds_read_b128 v[146:149], v154 offset:2048
	ds_read_b128 v[154:157], v154 offset:3072
	ds_read_b128 v[158:161], v170
	ds_read_b128 v[162:165], v170 offset:1024
	ds_read_b128 v[166:169], v170 offset:2048
	ds_read_b128 v[170:173], v170 offset:3072
	s_mov_b32 m0, s33
	ds_read_b128 v[174:177], v153 offset:32768
	ds_read_b128 v[178:181], v153 offset:33792
	ds_read_b128 v[182:185], v153 offset:34816
	ds_read_b128 v[186:189], v153 offset:35840
	ds_read_b128 v[190:193], v153 offset:36864
	ds_read_b128 v[194:197], v153 offset:37888
	ds_read_b128 v[198:201], v153 offset:38912
	ds_read_b128 v[202:205], v153 offset:39936
	s_add_u32 s98, s76, s8
	s_addc_u32 s99, s77, s9
	global_load_lds_dwordx4 v132, s[98:99]
	s_mov_b32 m0, s64
	s_nop 0
	s_add_u32 s98, s76, s10
	s_addc_u32 s99, s77, s11
	global_load_lds_dwordx4 v132, s[98:99]
	s_waitcnt vmcnt(8)
	s_waitcnt lgkmcnt(0)
	s_barrier
	s_setprio 1
	s_waitcnt lgkmcnt(0)
	v_mfma_f32_16x16x32_bf16 v[124:127], v[128:131], v[174:177], v[124:127]
	v_mfma_f32_16x16x32_bf16 v[124:127], v[142:145], v[178:181], v[124:127]
	v_mfma_f32_16x16x32_bf16 v[120:123], v[146:149], v[174:177], v[120:123]
	v_mfma_f32_16x16x32_bf16 v[120:123], v[154:157], v[178:181], v[120:123]
	v_mfma_f32_16x16x32_bf16 v[116:119], v[128:131], v[182:185], v[116:119]
	v_mfma_f32_16x16x32_bf16 v[116:119], v[142:145], v[186:189], v[116:119]
	v_mfma_f32_16x16x32_bf16 v[112:115], v[146:149], v[182:185], v[112:115]
	v_mfma_f32_16x16x32_bf16 v[112:115], v[154:157], v[186:189], v[112:115]
	v_mfma_f32_16x16x32_bf16 v[108:111], v[128:131], v[190:193], v[108:111]
	v_mfma_f32_16x16x32_bf16 v[108:111], v[142:145], v[194:197], v[108:111]
	v_mfma_f32_16x16x32_bf16 v[104:107], v[146:149], v[190:193], v[104:107]
	v_mfma_f32_16x16x32_bf16 v[104:107], v[154:157], v[194:197], v[104:107]
	v_mfma_f32_16x16x32_bf16 v[100:103], v[128:131], v[198:201], v[100:103]
	v_mfma_f32_16x16x32_bf16 v[100:103], v[142:145], v[202:205], v[100:103]
	v_mfma_f32_16x16x32_bf16 v[96:99], v[146:149], v[198:201], v[96:99]
	v_mfma_f32_16x16x32_bf16 v[96:99], v[154:157], v[202:205], v[96:99]
	s_setprio 0
	s_setprio 1
	v_mfma_f32_16x16x32_bf16 v[92:95], v[158:161], v[174:177], v[92:95]
	v_mfma_f32_16x16x32_bf16 v[92:95], v[162:165], v[178:181], v[92:95]
	v_mfma_f32_16x16x32_bf16 v[88:91], v[166:169], v[174:177], v[88:91]
	v_mfma_f32_16x16x32_bf16 v[88:91], v[170:173], v[178:181], v[88:91]
	v_mfma_f32_16x16x32_bf16 v[84:87], v[158:161], v[182:185], v[84:87]
	v_mfma_f32_16x16x32_bf16 v[84:87], v[162:165], v[186:189], v[84:87]
	v_mfma_f32_16x16x32_bf16 v[80:83], v[166:169], v[182:185], v[80:83]
	v_mfma_f32_16x16x32_bf16 v[80:83], v[170:173], v[186:189], v[80:83]
	s_setprio 2
	s_barrier
	v_mfma_f32_16x16x32_bf16 v[76:79], v[158:161], v[190:193], v[76:79]
	v_mfma_f32_16x16x32_bf16 v[76:79], v[162:165], v[194:197], v[76:79]
	v_mfma_f32_16x16x32_bf16 v[72:75], v[166:169], v[190:193], v[72:75]
	v_mfma_f32_16x16x32_bf16 v[72:75], v[170:173], v[194:197], v[72:75]
	v_mfma_f32_16x16x32_bf16 v[68:71], v[158:161], v[198:201], v[68:71]
	v_mfma_f32_16x16x32_bf16 v[68:71], v[162:165], v[202:205], v[68:71]
	v_mfma_f32_16x16x32_bf16 v[64:67], v[166:169], v[198:201], v[64:67]
	v_mfma_f32_16x16x32_bf16 v[64:67], v[170:173], v[202:205], v[64:67]
	s_setprio 0
	s_add_i32 s50, s50, s14
	s_mov_b32 m0, s50
	ds_read_b128 v[174:177], v153 offset:49152
	ds_read_b128 v[178:181], v153 offset:50176
	ds_read_b128 v[182:185], v153 offset:51200
	ds_read_b128 v[186:189], v153 offset:52224
	ds_read_b128 v[190:193], v153 offset:53248
	ds_read_b128 v[194:197], v153 offset:54272
	ds_read_b128 v[198:201], v153 offset:55296
	ds_read_b128 v[202:205], v153 offset:56320
	s_add_u32 s98, s78, s24
	s_addc_u32 s99, s79, s25
	global_load_lds_dwordx4 v134, s[98:99]
	s_add_i32 m0, s50, 0x2000
	s_add_i32 s50, s51, s14
	s_add_u32 s98, s78, s34
	s_addc_u32 s99, s79, s35
	global_load_lds_dwordx4 v134, s[98:99]
	s_mov_b32 m0, s50
	s_add_u32 s98, s78, s36
	s_addc_u32 s99, s79, s37
	global_load_lds_dwordx4 v134, s[98:99]
	s_add_i32 m0, s50, 0x2000
	s_nop 0
	s_add_u32 s98, s78, s38
	s_addc_u32 s99, s79, s39
	global_load_lds_dwordx4 v134, s[98:99]
	s_mov_b32 m0, s66
	s_nop 0
	s_add_u32 s98, s76, s24
	s_addc_u32 s99, s77, s25
	global_load_lds_dwordx4 v132, s[98:99]
	s_mov_b32 m0, s67
	s_nop 0
	s_add_u32 s98, s76, s34
	s_addc_u32 s99, s77, s35
	global_load_lds_dwordx4 v132, s[98:99]
	s_waitcnt vmcnt(8)
	s_waitcnt lgkmcnt(0)
	s_barrier
	s_setprio 1
	s_waitcnt lgkmcnt(0)
	v_mfma_f32_16x16x32_bf16 v[60:63], v[128:131], v[174:177], v[60:63]
	v_mfma_f32_16x16x32_bf16 v[60:63], v[142:145], v[178:181], v[60:63]
	v_mfma_f32_16x16x32_bf16 v[56:59], v[146:149], v[174:177], v[56:59]
	v_mfma_f32_16x16x32_bf16 v[56:59], v[154:157], v[178:181], v[56:59]
	v_mfma_f32_16x16x32_bf16 v[52:55], v[128:131], v[182:185], v[52:55]
	v_mfma_f32_16x16x32_bf16 v[52:55], v[142:145], v[186:189], v[52:55]
	v_mfma_f32_16x16x32_bf16 v[48:51], v[146:149], v[182:185], v[48:51]
	v_mfma_f32_16x16x32_bf16 v[48:51], v[154:157], v[186:189], v[48:51]
	v_mfma_f32_16x16x32_bf16 v[44:47], v[128:131], v[190:193], v[44:47]
	v_mfma_f32_16x16x32_bf16 v[44:47], v[142:145], v[194:197], v[44:47]
	v_mfma_f32_16x16x32_bf16 v[40:43], v[146:149], v[190:193], v[40:43]
	v_mfma_f32_16x16x32_bf16 v[40:43], v[154:157], v[194:197], v[40:43]
	v_mfma_f32_16x16x32_bf16 v[36:39], v[128:131], v[198:201], v[36:39]
	v_mfma_f32_16x16x32_bf16 v[36:39], v[142:145], v[202:205], v[36:39]
	v_mfma_f32_16x16x32_bf16 v[32:35], v[146:149], v[198:201], v[32:35]
	v_mfma_f32_16x16x32_bf16 v[32:35], v[154:157], v[202:205], v[32:35]
	s_setprio 0
	s_setprio 1
	v_mfma_f32_16x16x32_bf16 v[28:31], v[158:161], v[174:177], v[28:31]
	v_mfma_f32_16x16x32_bf16 v[28:31], v[162:165], v[178:181], v[28:31]
	v_mfma_f32_16x16x32_bf16 v[24:27], v[166:169], v[174:177], v[24:27]
	v_mfma_f32_16x16x32_bf16 v[24:27], v[170:173], v[178:181], v[24:27]
	v_mfma_f32_16x16x32_bf16 v[20:23], v[158:161], v[182:185], v[20:23]
	v_mfma_f32_16x16x32_bf16 v[20:23], v[162:165], v[186:189], v[20:23]
	v_mfma_f32_16x16x32_bf16 v[16:19], v[166:169], v[182:185], v[16:19]
	v_mfma_f32_16x16x32_bf16 v[16:19], v[170:173], v[186:189], v[16:19]
	s_setprio 2
	s_barrier
	v_mfma_f32_16x16x32_bf16 v[12:15], v[158:161], v[190:193], v[12:15]
	v_mfma_f32_16x16x32_bf16 v[12:15], v[162:165], v[194:197], v[12:15]
	v_mfma_f32_16x16x32_bf16 v[8:11], v[166:169], v[190:193], v[8:11]
	v_mfma_f32_16x16x32_bf16 v[8:11], v[170:173], v[194:197], v[8:11]
	v_mfma_f32_16x16x32_bf16 v[4:7], v[158:161], v[198:201], v[4:7]
	v_mfma_f32_16x16x32_bf16 v[4:7], v[162:165], v[202:205], v[4:7]
	v_mfma_f32_16x16x32_bf16 v[0:3], v[166:169], v[198:201], v[0:3]
	v_mfma_f32_16x16x32_bf16 v[0:3], v[170:173], v[202:205], v[0:3]
	s_setprio 0
	s_add_i32 s62, s62, 2
	s_add_u32 s74, s74, 0x100
	s_addc_u32 s75, s75, 0
	s_add_u32 s60, s60, 0x100
	s_addc_u32 s61, s61, 0
	s_cmp_gt_u32 s62, 61
	s_cbranch_scc0 .LBB0_627
	s_and_b64 vcc, exec, s[40:41]
	s_cbranch_vccz .LBB0_630
	s_barrier

.Lcm4_skip:
.LBB0_800:
	ds_read_b128 v[128:131], v187
	ds_read_b128 v[132:135], v187 offset:1024
	ds_read_b128 v[136:139], v187 offset:2048
	ds_read_b128 v[140:143], v187 offset:3072
	ds_read_b128 v[144:147], v188
	ds_read_b128 v[148:151], v188 offset:1024
	ds_read_b128 v[152:155], v188 offset:2048
	ds_read_b128 v[156:159], v188 offset:3072
	s_add_u32 s9, s6, 0xfff80080
	s_addc_u32 s50, s7, -1
	s_cmp_eq_u32 s8, 28
	s_cselect_b32 vcc_hi, s5, s50
	s_cselect_b32 vcc_lo, s10, s9
	s_cselect_b32 s51, s11, s78
	s_cselect_b32 s50, s73, s75
	s_add_i32 m0, s65, 0xc000
	ds_read_b128 v[160:163], v189
	ds_read_b128 v[164:167], v189 offset:1024
	ds_read_b128 v[168:171], v189 offset:2048
	ds_read_b128 v[192:195], v189 offset:3072
	ds_read_b128 v[196:199], v189 offset:4096
	ds_read_b128 v[200:203], v189 offset:5120
	ds_read_b128 v[204:207], v189 offset:6144
	ds_read_b128 v[208:211], v189 offset:7168
	global_load_lds_dwordx4 v178, s[6:7]
	s_add_i32 m0, s65, 0xe000
	s_nop 0
	s_add_u32 s98, s6, s36
	s_addc_u32 s99, s7, s37
	global_load_lds_dwordx4 v178, s[98:99]
	s_waitcnt vmcnt(8)
	s_waitcnt lgkmcnt(0)
	s_barrier
	s_setprio 1
	s_waitcnt lgkmcnt(0)
	v_mfma_i32_16x16x64_i8 v[84:87], v[128:131], v[160:163], v[84:87]
	v_mfma_i32_16x16x64_i8 v[84:87], v[132:135], v[164:167], v[84:87]
	v_mfma_i32_16x16x64_i8 v[16:19], v[136:139], v[160:163], v[16:19]
	v_mfma_i32_16x16x64_i8 v[16:19], v[140:143], v[164:167], v[16:19]
	v_mfma_i32_16x16x64_i8 v[88:91], v[128:131], v[168:171], v[88:91]
	v_mfma_i32_16x16x64_i8 v[88:91], v[132:135], v[192:195], v[88:91]
	v_mfma_i32_16x16x64_i8 v[20:23], v[136:139], v[168:171], v[20:23]
	v_mfma_i32_16x16x64_i8 v[20:23], v[140:143], v[192:195], v[20:23]
	v_mfma_i32_16x16x64_i8 v[92:95], v[128:131], v[196:199], v[92:95]
	v_mfma_i32_16x16x64_i8 v[92:95], v[132:135], v[200:203], v[92:95]
	v_mfma_i32_16x16x64_i8 v[24:27], v[136:139], v[196:199], v[24:27]
	v_mfma_i32_16x16x64_i8 v[24:27], v[140:143], v[200:203], v[24:27]
	v_mfma_i32_16x16x64_i8 v[96:99], v[128:131], v[204:207], v[96:99]
	v_mfma_i32_16x16x64_i8 v[96:99], v[132:135], v[208:211], v[96:99]
	v_mfma_i32_16x16x64_i8 v[28:31], v[136:139], v[204:207], v[28:31]
	v_mfma_i32_16x16x64_i8 v[28:31], v[140:143], v[208:211], v[28:31]
	s_setprio 0
	s_setprio 1
	v_mfma_i32_16x16x64_i8 v[124:127], v[144:147], v[160:163], v[124:127]
	v_mfma_i32_16x16x64_i8 v[124:127], v[148:151], v[164:167], v[124:127]
	v_mfma_i32_16x16x64_i8 v[68:71], v[152:155], v[160:163], v[68:71]
	v_mfma_i32_16x16x64_i8 v[68:71], v[156:159], v[164:167], v[68:71]
	v_mfma_i32_16x16x64_i8 v[120:123], v[144:147], v[168:171], v[120:123]
	v_mfma_i32_16x16x64_i8 v[120:123], v[148:151], v[192:195], v[120:123]
	v_mfma_i32_16x16x64_i8 v[72:75], v[152:155], v[168:171], v[72:75]
	v_mfma_i32_16x16x64_i8 v[72:75], v[156:159], v[192:195], v[72:75]
	s_setprio 2
	s_barrier
	v_mfma_i32_16x16x64_i8 v[116:119], v[144:147], v[196:199], v[116:119]
	v_mfma_i32_16x16x64_i8 v[116:119], v[148:151], v[200:203], v[116:119]
	v_mfma_i32_16x16x64_i8 v[80:83], v[152:155], v[196:199], v[80:83]
	v_mfma_i32_16x16x64_i8 v[80:83], v[156:159], v[200:203], v[80:83]
	v_mfma_i32_16x16x64_i8 v[112:115], v[144:147], v[204:207], v[112:115]
	v_mfma_i32_16x16x64_i8 v[112:115], v[148:151], v[208:211], v[112:115]
	v_mfma_i32_16x16x64_i8 v[60:63], v[152:155], v[204:207], v[60:63]
	v_mfma_i32_16x16x64_i8 v[60:63], v[156:159], v[208:211], v[60:63]
	s_setprio 0
	s_add_i32 s9, s80, s33
	s_mov_b64 s[100:101], s[50:51]
	s_mov_b32 m0, s9
	ds_read_b128 v[160:163], v189 offset:16384
	ds_read_b128 v[164:167], v189 offset:17408
	ds_read_b128 v[168:171], v189 offset:18432
	ds_read_b128 v[192:195], v189 offset:19456
	ds_read_b128 v[196:199], v189 offset:20480
	ds_read_b128 v[200:203], v189 offset:21504
	ds_read_b128 v[204:207], v189 offset:22528
	ds_read_b128 v[208:211], v189 offset:23552
	global_load_lds_dwordx4 v174, s[50:51]
	s_add_i32 m0, s9, 0x2000
	s_add_i32 s9, s81, s33
	s_add_u32 s98, s50, s36
	s_addc_u32 s99, s51, s37
	global_load_lds_dwordx4 v174, s[98:99]
	s_mov_b32 m0, s9
	s_nop 0
	s_add_u32 s98, s50, s38
	s_addc_u32 s99, s51, s39
	global_load_lds_dwordx4 v174, s[98:99]
	s_add_i32 m0, s9, 0x2000
	s_nop 0
	s_add_u32 s98, s50, s40
	s_addc_u32 s99, s51, s41
	global_load_lds_dwordx4 v174, s[98:99]
	s_mov_b32 m0, s65
	s_nop 0
	global_load_lds_dwordx4 v172, vcc
	s_mov_b32 m0, s67
	s_nop 0
	s_add_u32 s98, vcc_lo, s36
	s_addc_u32 s99, vcc_hi, s37
	global_load_lds_dwordx4 v172, s[98:99]
	s_waitcnt vmcnt(8)
	s_waitcnt lgkmcnt(0)
	s_barrier
	s_setprio 1
	s_waitcnt lgkmcnt(0)
	v_mfma_i32_16x16x64_i8 v[48:51], v[128:131], v[160:163], v[48:51]
	v_mfma_i32_16x16x64_i8 v[48:51], v[132:135], v[164:167], v[48:51]
	v_mfma_i32_16x16x64_i8 v[0:3], v[136:139], v[160:163], v[0:3]
	v_mfma_i32_16x16x64_i8 v[0:3], v[140:143], v[164:167], v[0:3]
	v_mfma_i32_16x16x64_i8 v[52:55], v[128:131], v[168:171], v[52:55]
	v_mfma_i32_16x16x64_i8 v[52:55], v[132:135], v[192:195], v[52:55]
	v_mfma_i32_16x16x64_i8 v[4:7], v[136:139], v[168:171], v[4:7]
	v_mfma_i32_16x16x64_i8 v[4:7], v[140:143], v[192:195], v[4:7]
	v_mfma_i32_16x16x64_i8 v[56:59], v[128:131], v[196:199], v[56:59]
	v_mfma_i32_16x16x64_i8 v[56:59], v[132:135], v[200:203], v[56:59]
	v_mfma_i32_16x16x64_i8 v[8:11], v[136:139], v[196:199], v[8:11]
	v_mfma_i32_16x16x64_i8 v[8:11], v[140:143], v[200:203], v[8:11]
	v_mfma_i32_16x16x64_i8 v[64:67], v[128:131], v[204:207], v[64:67]
	v_mfma_i32_16x16x64_i8 v[64:67], v[132:135], v[208:211], v[64:67]
	v_mfma_i32_16x16x64_i8 v[12:15], v[136:139], v[204:207], v[12:15]
	v_mfma_i32_16x16x64_i8 v[12:15], v[140:143], v[208:211], v[12:15]
	s_setprio 0
	s_setprio 1
	v_mfma_i32_16x16x64_i8 v[108:111], v[144:147], v[160:163], v[108:111]
	v_mfma_i32_16x16x64_i8 v[108:111], v[148:151], v[164:167], v[108:111]
	v_mfma_i32_16x16x64_i8 v[44:47], v[152:155], v[160:163], v[44:47]
	v_mfma_i32_16x16x64_i8 v[44:47], v[156:159], v[164:167], v[44:47]
	v_mfma_i32_16x16x64_i8 v[104:107], v[144:147], v[168:171], v[104:107]
	v_mfma_i32_16x16x64_i8 v[104:107], v[148:151], v[192:195], v[104:107]
	v_mfma_i32_16x16x64_i8 v[40:43], v[152:155], v[168:171], v[40:43]
	v_mfma_i32_16x16x64_i8 v[40:43], v[156:159], v[192:195], v[40:43]
	s_setprio 2
	s_barrier
	v_mfma_i32_16x16x64_i8 v[100:103], v[144:147], v[196:199], v[100:103]
	v_mfma_i32_16x16x64_i8 v[100:103], v[148:151], v[200:203], v[100:103]
	v_mfma_i32_16x16x64_i8 v[32:35], v[152:155], v[196:199], v[32:35]
	v_mfma_i32_16x16x64_i8 v[32:35], v[156:159], v[200:203], v[32:35]
	v_mfma_i32_16x16x64_i8 v[76:79], v[144:147], v[204:207], v[76:79]
	v_mfma_i32_16x16x64_i8 v[76:79], v[148:151], v[208:211], v[76:79]
	v_mfma_i32_16x16x64_i8 v[36:39], v[152:155], v[204:207], v[36:39]
	v_mfma_i32_16x16x64_i8 v[36:39], v[156:159], v[208:211], v[36:39]
	s_setprio 0
	s_add_i32 s9, 0, 0x18000
	s_add_i32 s50, 0, 0x1c000
	v_add_u32_e32 v140, s9, v186
	v_add_u32_e32 v156, s50, v186
	ds_read_b128 v[128:131], v140
	ds_read_b128 v[132:135], v140 offset:1024
	ds_read_b128 v[136:139], v140 offset:2048
	ds_read_b128 v[140:143], v140 offset:3072
	ds_read_b128 v[144:147], v156
	ds_read_b128 v[148:151], v156 offset:1024
	ds_read_b128 v[152:155], v156 offset:2048
	ds_read_b128 v[156:159], v156 offset:3072
	s_mov_b32 m0, s71
	ds_read_b128 v[160:163], v189 offset:32768
	ds_read_b128 v[164:167], v189 offset:33792
	ds_read_b128 v[168:171], v189 offset:34816
	ds_read_b128 v[192:195], v189 offset:35840
	ds_read_b128 v[196:199], v189 offset:36864
	ds_read_b128 v[200:203], v189 offset:37888
	ds_read_b128 v[204:207], v189 offset:38912
	ds_read_b128 v[208:211], v189 offset:39936
	s_add_u32 s98, vcc_lo, s38
	s_addc_u32 s99, vcc_hi, s39
	global_load_lds_dwordx4 v172, s[98:99]
	s_mov_b32 m0, s82
	s_nop 0
	s_add_u32 s98, vcc_lo, s40
	s_addc_u32 s99, vcc_hi, s41
	global_load_lds_dwordx4 v172, s[98:99]
	s_waitcnt vmcnt(8)
	s_waitcnt lgkmcnt(0)
	s_barrier
	s_setprio 1
	s_waitcnt lgkmcnt(0)
	v_mfma_i32_16x16x64_i8 v[84:87], v[128:131], v[160:163], v[84:87]
	v_mfma_i32_16x16x64_i8 v[84:87], v[132:135], v[164:167], v[84:87]
	v_mfma_i32_16x16x64_i8 v[16:19], v[136:139], v[160:163], v[16:19]
	v_mfma_i32_16x16x64_i8 v[16:19], v[140:143], v[164:167], v[16:19]
	v_mfma_i32_16x16x64_i8 v[88:91], v[128:131], v[168:171], v[88:91]
	v_mfma_i32_16x16x64_i8 v[88:91], v[132:135], v[192:195], v[88:91]
	v_mfma_i32_16x16x64_i8 v[20:23], v[136:139], v[168:171], v[20:23]
	v_mfma_i32_16x16x64_i8 v[20:23], v[140:143], v[192:195], v[20:23]
	v_mfma_i32_16x16x64_i8 v[92:95], v[128:131], v[196:199], v[92:95]
	v_mfma_i32_16x16x64_i8 v[92:95], v[132:135], v[200:203], v[92:95]
	v_mfma_i32_16x16x64_i8 v[24:27], v[136:139], v[196:199], v[24:27]
	v_mfma_i32_16x16x64_i8 v[24:27], v[140:143], v[200:203], v[24:27]
	v_mfma_i32_16x16x64_i8 v[96:99], v[128:131], v[204:207], v[96:99]
	v_mfma_i32_16x16x64_i8 v[96:99], v[132:135], v[208:211], v[96:99]
	v_mfma_i32_16x16x64_i8 v[28:31], v[136:139], v[204:207], v[28:31]
	v_mfma_i32_16x16x64_i8 v[28:31], v[140:143], v[208:211], v[28:31]
	s_setprio 0
	s_setprio 1
	v_mfma_i32_16x16x64_i8 v[124:127], v[144:147], v[160:163], v[124:127]
	v_mfma_i32_16x16x64_i8 v[124:127], v[148:151], v[164:167], v[124:127]
	v_mfma_i32_16x16x64_i8 v[68:71], v[152:155], v[160:163], v[68:71]
	v_mfma_i32_16x16x64_i8 v[68:71], v[156:159], v[164:167], v[68:71]
	v_mfma_i32_16x16x64_i8 v[120:123], v[144:147], v[168:171], v[120:123]
	v_mfma_i32_16x16x64_i8 v[120:123], v[148:151], v[192:195], v[120:123]
	v_mfma_i32_16x16x64_i8 v[72:75], v[152:155], v[168:171], v[72:75]
	v_mfma_i32_16x16x64_i8 v[72:75], v[156:159], v[192:195], v[72:75]
	s_setprio 2
	s_barrier
	v_mfma_i32_16x16x64_i8 v[116:119], v[144:147], v[196:199], v[116:119]
	v_mfma_i32_16x16x64_i8 v[116:119], v[148:151], v[200:203], v[116:119]
	v_mfma_i32_16x16x64_i8 v[80:83], v[152:155], v[196:199], v[80:83]
	v_mfma_i32_16x16x64_i8 v[80:83], v[156:159], v[200:203], v[80:83]
	v_mfma_i32_16x16x64_i8 v[112:115], v[144:147], v[204:207], v[112:115]
	v_mfma_i32_16x16x64_i8 v[112:115], v[148:151], v[208:211], v[112:115]
	v_mfma_i32_16x16x64_i8 v[60:63], v[152:155], v[204:207], v[60:63]
	v_mfma_i32_16x16x64_i8 v[60:63], v[156:159], v[208:211], v[60:63]
	s_setprio 0
	s_add_i32 s9, s9, s33
	s_mov_b32 m0, s9
	ds_read_b128 v[160:163], v189 offset:49152
	ds_read_b128 v[164:167], v189 offset:50176
	ds_read_b128 v[168:171], v189 offset:51200
	ds_read_b128 v[192:195], v189 offset:52224
	ds_read_b128 v[196:199], v189 offset:53248
	ds_read_b128 v[200:203], v189 offset:54272
	ds_read_b128 v[204:207], v189 offset:55296
	ds_read_b128 v[208:211], v189 offset:56320
	s_add_u32 s98, s100, s44
	s_addc_u32 s99, s101, s45
	global_load_lds_dwordx4 v174, s[98:99]
	s_add_i32 m0, s9, 0x2000
	s_add_i32 s9, s50, s33
	s_add_u32 s98, s100, s46
	s_addc_u32 s99, s101, s47
	global_load_lds_dwordx4 v174, s[98:99]
	s_mov_b32 m0, s9
	s_add_u32 s98, s100, s48
	s_addc_u32 s99, s101, s49
	global_load_lds_dwordx4 v174, s[98:99]
	s_add_i32 m0, s9, 0x2000
	s_nop 0
	s_add_u32 s98, s100, s52
	s_addc_u32 s99, s101, s53
	global_load_lds_dwordx4 v174, s[98:99]
	s_mov_b32 m0, s90
	s_nop 0
	s_add_u32 s98, vcc_lo, s44
	s_addc_u32 s99, vcc_hi, s45
	global_load_lds_dwordx4 v172, s[98:99]
	s_mov_b32 m0, s91
	s_nop 0
	s_add_u32 s98, vcc_lo, s46
	s_addc_u32 s99, vcc_hi, s47
	global_load_lds_dwordx4 v172, s[98:99]
	s_waitcnt vmcnt(8)
	s_waitcnt lgkmcnt(0)
	s_barrier
	s_setprio 1
	s_waitcnt lgkmcnt(0)
	v_mfma_i32_16x16x64_i8 v[48:51], v[128:131], v[160:163], v[48:51]
	v_mfma_i32_16x16x64_i8 v[48:51], v[132:135], v[164:167], v[48:51]
	v_mfma_i32_16x16x64_i8 v[0:3], v[136:139], v[160:163], v[0:3]
	v_mfma_i32_16x16x64_i8 v[0:3], v[140:143], v[164:167], v[0:3]
	v_mfma_i32_16x16x64_i8 v[52:55], v[128:131], v[168:171], v[52:55]
	v_mfma_i32_16x16x64_i8 v[52:55], v[132:135], v[192:195], v[52:55]
	v_mfma_i32_16x16x64_i8 v[4:7], v[136:139], v[168:171], v[4:7]
	v_mfma_i32_16x16x64_i8 v[4:7], v[140:143], v[192:195], v[4:7]
	v_mfma_i32_16x16x64_i8 v[56:59], v[128:131], v[196:199], v[56:59]
	v_mfma_i32_16x16x64_i8 v[56:59], v[132:135], v[200:203], v[56:59]
	v_mfma_i32_16x16x64_i8 v[8:11], v[136:139], v[196:199], v[8:11]
	v_mfma_i32_16x16x64_i8 v[8:11], v[140:143], v[200:203], v[8:11]
	v_mfma_i32_16x16x64_i8 v[64:67], v[128:131], v[204:207], v[64:67]
	v_mfma_i32_16x16x64_i8 v[64:67], v[132:135], v[208:211], v[64:67]
	v_mfma_i32_16x16x64_i8 v[12:15], v[136:139], v[204:207], v[12:15]
	v_mfma_i32_16x16x64_i8 v[12:15], v[140:143], v[208:211], v[12:15]
	s_setprio 0
	s_setprio 1
	v_mfma_i32_16x16x64_i8 v[108:111], v[144:147], v[160:163], v[108:111]
	v_mfma_i32_16x16x64_i8 v[108:111], v[148:151], v[164:167], v[108:111]
	v_mfma_i32_16x16x64_i8 v[44:47], v[152:155], v[160:163], v[44:47]
	v_mfma_i32_16x16x64_i8 v[44:47], v[156:159], v[164:167], v[44:47]
	v_mfma_i32_16x16x64_i8 v[104:107], v[144:147], v[168:171], v[104:107]
	v_mfma_i32_16x16x64_i8 v[104:107], v[148:151], v[192:195], v[104:107]
	v_mfma_i32_16x16x64_i8 v[40:43], v[152:155], v[168:171], v[40:43]
	v_mfma_i32_16x16x64_i8 v[40:43], v[156:159], v[192:195], v[40:43]
	s_setprio 2
	s_barrier
	v_mfma_i32_16x16x64_i8 v[100:103], v[144:147], v[196:199], v[100:103]
	v_mfma_i32_16x16x64_i8 v[100:103], v[148:151], v[200:203], v[100:103]
	v_mfma_i32_16x16x64_i8 v[32:35], v[152:155], v[196:199], v[32:35]
	v_mfma_i32_16x16x64_i8 v[32:35], v[156:159], v[200:203], v[32:35]
	v_mfma_i32_16x16x64_i8 v[76:79], v[144:147], v[204:207], v[76:79]
	v_mfma_i32_16x16x64_i8 v[76:79], v[148:151], v[208:211], v[76:79]
	v_mfma_i32_16x16x64_i8 v[36:39], v[152:155], v[204:207], v[36:39]
	v_mfma_i32_16x16x64_i8 v[36:39], v[156:159], v[208:211], v[36:39]
	s_setprio 0
	s_add_i32 s8, s8, 2
	s_add_u32 s75, s75, 0x100
	s_addc_u32 s78, s78, 0
	s_add_u32 s6, s6, 0x100
	s_addc_u32 s7, s7, 0
	s_cmp_gt_u32 s8, 29
	s_cbranch_scc0 .LBB0_800
	s_and_b64 vcc, exec, s[54:55]
	s_cbranch_vccz .LBB0_803
	s_barrier

.LBB0_1034:
	ds_read_b128 v[138:141], v151
	ds_read_b128 v[142:145], v151 offset:1024
	ds_read_b128 v[146:149], v151 offset:2048
	ds_read_b128 v[154:157], v151 offset:3072
	ds_read_b128 v[158:161], v152
	ds_read_b128 v[162:165], v152 offset:1024
	ds_read_b128 v[166:169], v152 offset:2048
	ds_read_b128 v[170:173], v152 offset:3072
	s_add_u32 s47, s44, 0xffd50080
	s_addc_u32 s64, s45, -1
	s_cmpk_eq_i32 s46, 0xa8
	s_cselect_b32 s65, s5, s64
	s_cselect_b32 s64, s4, s47
	s_cselect_b32 s67, s43, s63
	s_cselect_b32 s66, s42, s62
	s_add_i32 m0, s25, 0xc000
	ds_read_b128 v[174:177], v153
	ds_read_b128 v[178:181], v153 offset:1024
	ds_read_b128 v[182:185], v153 offset:2048
	ds_read_b128 v[186:189], v153 offset:3072
	ds_read_b128 v[190:193], v153 offset:4096
	ds_read_b128 v[194:197], v153 offset:5120
	ds_read_b128 v[198:201], v153 offset:6144
	ds_read_b128 v[202:205], v153 offset:7168
	global_load_lds_dwordx4 v132, s[44:45]
	s_add_i32 m0, s25, 0xe000
	s_nop 0
	s_add_u32 s98, s44, s0
	s_addc_u32 s99, s45, s1
	global_load_lds_dwordx4 v132, s[98:99]
	s_waitcnt vmcnt(8)
	s_waitcnt lgkmcnt(0)
	s_barrier
	s_setprio 1
	s_waitcnt lgkmcnt(0)
	v_mfma_f32_16x16x32_bf16 v[124:127], v[138:141], v[174:177], v[124:127]
	v_mfma_f32_16x16x32_bf16 v[124:127], v[142:145], v[178:181], v[124:127]
	v_mfma_f32_16x16x32_bf16 v[120:123], v[146:149], v[174:177], v[120:123]
	v_mfma_f32_16x16x32_bf16 v[120:123], v[154:157], v[178:181], v[120:123]
	v_mfma_f32_16x16x32_bf16 v[116:119], v[138:141], v[182:185], v[116:119]
	v_mfma_f32_16x16x32_bf16 v[116:119], v[142:145], v[186:189], v[116:119]
	v_mfma_f32_16x16x32_bf16 v[112:115], v[146:149], v[182:185], v[112:115]
	v_mfma_f32_16x16x32_bf16 v[112:115], v[154:157], v[186:189], v[112:115]
	v_mfma_f32_16x16x32_bf16 v[108:111], v[138:141], v[190:193], v[108:111]
	v_mfma_f32_16x16x32_bf16 v[108:111], v[142:145], v[194:197], v[108:111]
	v_mfma_f32_16x16x32_bf16 v[104:107], v[146:149], v[190:193], v[104:107]
	v_mfma_f32_16x16x32_bf16 v[104:107], v[154:157], v[194:197], v[104:107]
	v_mfma_f32_16x16x32_bf16 v[100:103], v[138:141], v[198:201], v[100:103]
	v_mfma_f32_16x16x32_bf16 v[100:103], v[142:145], v[202:205], v[100:103]
	v_mfma_f32_16x16x32_bf16 v[96:99], v[146:149], v[198:201], v[96:99]
	v_mfma_f32_16x16x32_bf16 v[96:99], v[154:157], v[202:205], v[96:99]
	s_setprio 0
	s_setprio 1
	v_mfma_f32_16x16x32_bf16 v[92:95], v[158:161], v[174:177], v[92:95]
	v_mfma_f32_16x16x32_bf16 v[92:95], v[162:165], v[178:181], v[92:95]
	v_mfma_f32_16x16x32_bf16 v[88:91], v[166:169], v[174:177], v[88:91]
	v_mfma_f32_16x16x32_bf16 v[88:91], v[170:173], v[178:181], v[88:91]
	v_mfma_f32_16x16x32_bf16 v[84:87], v[158:161], v[182:185], v[84:87]
	v_mfma_f32_16x16x32_bf16 v[84:87], v[162:165], v[186:189], v[84:87]
	v_mfma_f32_16x16x32_bf16 v[80:83], v[166:169], v[182:185], v[80:83]
	v_mfma_f32_16x16x32_bf16 v[80:83], v[170:173], v[186:189], v[80:83]
	s_setprio 2
	s_barrier
	v_mfma_f32_16x16x32_bf16 v[76:79], v[158:161], v[190:193], v[76:79]
	v_mfma_f32_16x16x32_bf16 v[76:79], v[162:165], v[194:197], v[76:79]
	v_mfma_f32_16x16x32_bf16 v[72:75], v[166:169], v[190:193], v[72:75]
	v_mfma_f32_16x16x32_bf16 v[72:75], v[170:173], v[194:197], v[72:75]
	v_mfma_f32_16x16x32_bf16 v[68:71], v[158:161], v[198:201], v[68:71]
	v_mfma_f32_16x16x32_bf16 v[68:71], v[162:165], v[202:205], v[68:71]
	v_mfma_f32_16x16x32_bf16 v[64:67], v[166:169], v[198:201], v[64:67]
	v_mfma_f32_16x16x32_bf16 v[64:67], v[170:173], v[202:205], v[64:67]
	s_setprio 0
	s_add_i32 s47, s56, s24
	s_mov_b32 m0, s47
	ds_read_b128 v[174:177], v153 offset:16384
	ds_read_b128 v[178:181], v153 offset:17408
	ds_read_b128 v[182:185], v153 offset:18432
	ds_read_b128 v[186:189], v153 offset:19456
	ds_read_b128 v[190:193], v153 offset:20480
	ds_read_b128 v[194:197], v153 offset:21504
	ds_read_b128 v[198:201], v153 offset:22528
	ds_read_b128 v[202:205], v153 offset:23552
	global_load_lds_dwordx4 v130, s[66:67]
	s_add_i32 m0, s47, 0x2000
	s_add_i32 s47, s57, s24
	s_add_u32 s98, s66, s0
	s_addc_u32 s99, s67, s1
	global_load_lds_dwordx4 v130, s[98:99]
	s_mov_b32 m0, s47
	s_nop 0
	s_add_u32 s98, s66, s6
	s_addc_u32 s99, s67, s7
	global_load_lds_dwordx4 v130, s[98:99]
	s_add_i32 m0, s47, 0x2000
	s_nop 0
	s_add_u32 s98, s66, s8
	s_addc_u32 s99, s67, s9
	global_load_lds_dwordx4 v130, s[98:99]
	s_mov_b64 s[100:101], s[64:65]
	s_mov_b32 m0, s25
	s_nop 0
	global_load_lds_dwordx4 v128, s[64:65]
	s_mov_b32 m0, s33
	s_nop 0
	s_add_u32 s98, s64, s0
	s_addc_u32 s99, s65, s1
	global_load_lds_dwordx4 v128, s[98:99]
	s_waitcnt vmcnt(8)
	s_waitcnt lgkmcnt(0)
	s_barrier
	s_setprio 1
	s_waitcnt lgkmcnt(0)
	v_mfma_f32_16x16x32_bf16 v[60:63], v[138:141], v[174:177], v[60:63]
	v_mfma_f32_16x16x32_bf16 v[60:63], v[142:145], v[178:181], v[60:63]
	v_mfma_f32_16x16x32_bf16 v[56:59], v[146:149], v[174:177], v[56:59]
	v_mfma_f32_16x16x32_bf16 v[56:59], v[154:157], v[178:181], v[56:59]
	v_mfma_f32_16x16x32_bf16 v[52:55], v[138:141], v[182:185], v[52:55]
	v_mfma_f32_16x16x32_bf16 v[52:55], v[142:145], v[186:189], v[52:55]
	v_mfma_f32_16x16x32_bf16 v[48:51], v[146:149], v[182:185], v[48:51]
	v_mfma_f32_16x16x32_bf16 v[48:51], v[154:157], v[186:189], v[48:51]
	v_mfma_f32_16x16x32_bf16 v[44:47], v[138:141], v[190:193], v[44:47]
	v_mfma_f32_16x16x32_bf16 v[44:47], v[142:145], v[194:197], v[44:47]
	v_mfma_f32_16x16x32_bf16 v[40:43], v[146:149], v[190:193], v[40:43]
	v_mfma_f32_16x16x32_bf16 v[40:43], v[154:157], v[194:197], v[40:43]
	v_mfma_f32_16x16x32_bf16 v[36:39], v[138:141], v[198:201], v[36:39]
	v_mfma_f32_16x16x32_bf16 v[36:39], v[142:145], v[202:205], v[36:39]
	v_mfma_f32_16x16x32_bf16 v[32:35], v[146:149], v[198:201], v[32:35]
	v_mfma_f32_16x16x32_bf16 v[32:35], v[154:157], v[202:205], v[32:35]
	s_setprio 0
	s_setprio 1
	v_mfma_f32_16x16x32_bf16 v[28:31], v[158:161], v[174:177], v[28:31]
	v_mfma_f32_16x16x32_bf16 v[28:31], v[162:165], v[178:181], v[28:31]
	v_mfma_f32_16x16x32_bf16 v[24:27], v[166:169], v[174:177], v[24:27]
	v_mfma_f32_16x16x32_bf16 v[24:27], v[170:173], v[178:181], v[24:27]
	v_mfma_f32_16x16x32_bf16 v[20:23], v[158:161], v[182:185], v[20:23]
	v_mfma_f32_16x16x32_bf16 v[20:23], v[162:165], v[186:189], v[20:23]
	v_mfma_f32_16x16x32_bf16 v[16:19], v[166:169], v[182:185], v[16:19]
	v_mfma_f32_16x16x32_bf16 v[16:19], v[170:173], v[186:189], v[16:19]
	s_setprio 2
	s_barrier
	v_mfma_f32_16x16x32_bf16 v[12:15], v[158:161], v[190:193], v[12:15]
	v_mfma_f32_16x16x32_bf16 v[12:15], v[162:165], v[194:197], v[12:15]
	v_mfma_f32_16x16x32_bf16 v[8:11], v[166:169], v[190:193], v[8:11]
	v_mfma_f32_16x16x32_bf16 v[8:11], v[170:173], v[194:197], v[8:11]
	v_mfma_f32_16x16x32_bf16 v[4:7], v[158:161], v[198:201], v[4:7]
	v_mfma_f32_16x16x32_bf16 v[4:7], v[162:165], v[202:205], v[4:7]
	v_mfma_f32_16x16x32_bf16 v[0:3], v[166:169], v[198:201], v[0:3]
	v_mfma_f32_16x16x32_bf16 v[0:3], v[170:173], v[202:205], v[0:3]
	s_setprio 0
	s_add_i32 s47, 0, 0x18000
	s_add_i32 s64, 0, 0x1c000
	v_add_u32_e32 v154, s47, v150
	v_add_u32_e32 v170, s64, v150
	ds_read_b128 v[138:141], v154
	ds_read_b128 v[142:145], v154 offset:1024
	ds_read_b128 v[146:149], v154 offset:2048
	ds_read_b128 v[154:157], v154 offset:3072
	ds_read_b128 v[158:161], v170
	ds_read_b128 v[162:165], v170 offset:1024
	ds_read_b128 v[166:169], v170 offset:2048
	ds_read_b128 v[170:173], v170 offset:3072
	s_mov_b32 m0, s48
	ds_read_b128 v[174:177], v153 offset:32768
	ds_read_b128 v[178:181], v153 offset:33792
	ds_read_b128 v[182:185], v153 offset:34816
	ds_read_b128 v[186:189], v153 offset:35840
	ds_read_b128 v[190:193], v153 offset:36864
	ds_read_b128 v[194:197], v153 offset:37888
	ds_read_b128 v[198:201], v153 offset:38912
	ds_read_b128 v[202:205], v153 offset:39936
	s_add_u32 s98, s100, s6
	s_addc_u32 s99, s101, s7
	global_load_lds_dwordx4 v128, s[98:99]
	s_mov_b32 m0, s49
	s_nop 0
	s_add_u32 s98, s100, s8
	s_addc_u32 s99, s101, s9
	global_load_lds_dwordx4 v128, s[98:99]
	s_waitcnt vmcnt(8)
	s_waitcnt lgkmcnt(0)
	s_barrier
	s_setprio 1
	s_waitcnt lgkmcnt(0)
	v_mfma_f32_16x16x32_bf16 v[124:127], v[138:141], v[174:177], v[124:127]
	v_mfma_f32_16x16x32_bf16 v[124:127], v[142:145], v[178:181], v[124:127]
	v_mfma_f32_16x16x32_bf16 v[120:123], v[146:149], v[174:177], v[120:123]
	v_mfma_f32_16x16x32_bf16 v[120:123], v[154:157], v[178:181], v[120:123]
	v_mfma_f32_16x16x32_bf16 v[116:119], v[138:141], v[182:185], v[116:119]
	v_mfma_f32_16x16x32_bf16 v[116:119], v[142:145], v[186:189], v[116:119]
	v_mfma_f32_16x16x32_bf16 v[112:115], v[146:149], v[182:185], v[112:115]
	v_mfma_f32_16x16x32_bf16 v[112:115], v[154:157], v[186:189], v[112:115]
	v_mfma_f32_16x16x32_bf16 v[108:111], v[138:141], v[190:193], v[108:111]
	v_mfma_f32_16x16x32_bf16 v[108:111], v[142:145], v[194:197], v[108:111]
	v_mfma_f32_16x16x32_bf16 v[104:107], v[146:149], v[190:193], v[104:107]
	v_mfma_f32_16x16x32_bf16 v[104:107], v[154:157], v[194:197], v[104:107]
	v_mfma_f32_16x16x32_bf16 v[100:103], v[138:141], v[198:201], v[100:103]
	v_mfma_f32_16x16x32_bf16 v[100:103], v[142:145], v[202:205], v[100:103]
	v_mfma_f32_16x16x32_bf16 v[96:99], v[146:149], v[198:201], v[96:99]
	v_mfma_f32_16x16x32_bf16 v[96:99], v[154:157], v[202:205], v[96:99]
	s_setprio 0
	s_setprio 1
	v_mfma_f32_16x16x32_bf16 v[92:95], v[158:161], v[174:177], v[92:95]
	v_mfma_f32_16x16x32_bf16 v[92:95], v[162:165], v[178:181], v[92:95]
	v_mfma_f32_16x16x32_bf16 v[88:91], v[166:169], v[174:177], v[88:91]
	v_mfma_f32_16x16x32_bf16 v[88:91], v[170:173], v[178:181], v[88:91]
	v_mfma_f32_16x16x32_bf16 v[84:87], v[158:161], v[182:185], v[84:87]
	v_mfma_f32_16x16x32_bf16 v[84:87], v[162:165], v[186:189], v[84:87]
	v_mfma_f32_16x16x32_bf16 v[80:83], v[166:169], v[182:185], v[80:83]
	v_mfma_f32_16x16x32_bf16 v[80:83], v[170:173], v[186:189], v[80:83]
	s_setprio 2
	s_barrier
	v_mfma_f32_16x16x32_bf16 v[76:79], v[158:161], v[190:193], v[76:79]
	v_mfma_f32_16x16x32_bf16 v[76:79], v[162:165], v[194:197], v[76:79]
	v_mfma_f32_16x16x32_bf16 v[72:75], v[166:169], v[190:193], v[72:75]
	v_mfma_f32_16x16x32_bf16 v[72:75], v[170:173], v[194:197], v[72:75]
	v_mfma_f32_16x16x32_bf16 v[68:71], v[158:161], v[198:201], v[68:71]
	v_mfma_f32_16x16x32_bf16 v[68:71], v[162:165], v[202:205], v[68:71]
	v_mfma_f32_16x16x32_bf16 v[64:67], v[166:169], v[198:201], v[64:67]
	v_mfma_f32_16x16x32_bf16 v[64:67], v[170:173], v[202:205], v[64:67]
	s_setprio 0
	s_add_i32 s47, s47, s24
	s_mov_b32 m0, s47
	ds_read_b128 v[174:177], v153 offset:49152
	ds_read_b128 v[178:181], v153 offset:50176
	ds_read_b128 v[182:185], v153 offset:51200
	ds_read_b128 v[186:189], v153 offset:52224
	ds_read_b128 v[190:193], v153 offset:53248
	ds_read_b128 v[194:197], v153 offset:54272
	ds_read_b128 v[198:201], v153 offset:55296
	ds_read_b128 v[202:205], v153 offset:56320
	s_add_u32 s98, s66, s16
	s_addc_u32 s99, s67, s17
	global_load_lds_dwordx4 v130, s[98:99]
	s_add_i32 m0, s47, 0x2000
	s_add_i32 s47, s64, s24
	s_add_u32 s98, s66, s20
	s_addc_u32 s99, s67, s21
	global_load_lds_dwordx4 v130, s[98:99]
	s_mov_b32 m0, s47
	s_add_u32 s98, s66, s34
	s_addc_u32 s99, s67, s35
	global_load_lds_dwordx4 v130, s[98:99]
	s_add_i32 m0, s47, 0x2000
	s_nop 0
	s_add_u32 s98, s66, s36
	s_addc_u32 s99, s67, s37
	global_load_lds_dwordx4 v130, s[98:99]
	s_mov_b32 m0, s51
	s_nop 0
	s_add_u32 s98, s100, s16
	s_addc_u32 s99, s101, s17
	global_load_lds_dwordx4 v128, s[98:99]
	s_mov_b32 m0, s52
	s_nop 0
	s_add_u32 s98, s100, s20
	s_addc_u32 s99, s101, s21
	global_load_lds_dwordx4 v128, s[98:99]
	s_waitcnt vmcnt(8)
	s_waitcnt lgkmcnt(0)
	s_barrier
	s_setprio 1
	s_waitcnt lgkmcnt(0)
	v_mfma_f32_16x16x32_bf16 v[60:63], v[138:141], v[174:177], v[60:63]
	v_mfma_f32_16x16x32_bf16 v[60:63], v[142:145], v[178:181], v[60:63]
	v_mfma_f32_16x16x32_bf16 v[56:59], v[146:149], v[174:177], v[56:59]
	v_mfma_f32_16x16x32_bf16 v[56:59], v[154:157], v[178:181], v[56:59]
	v_mfma_f32_16x16x32_bf16 v[52:55], v[138:141], v[182:185], v[52:55]
	v_mfma_f32_16x16x32_bf16 v[52:55], v[142:145], v[186:189], v[52:55]
	v_mfma_f32_16x16x32_bf16 v[48:51], v[146:149], v[182:185], v[48:51]
	v_mfma_f32_16x16x32_bf16 v[48:51], v[154:157], v[186:189], v[48:51]
	v_mfma_f32_16x16x32_bf16 v[44:47], v[138:141], v[190:193], v[44:47]
	v_mfma_f32_16x16x32_bf16 v[44:47], v[142:145], v[194:197], v[44:47]
	v_mfma_f32_16x16x32_bf16 v[40:43], v[146:149], v[190:193], v[40:43]
	v_mfma_f32_16x16x32_bf16 v[40:43], v[154:157], v[194:197], v[40:43]
	v_mfma_f32_16x16x32_bf16 v[36:39], v[138:141], v[198:201], v[36:39]
	v_mfma_f32_16x16x32_bf16 v[36:39], v[142:145], v[202:205], v[36:39]
	v_mfma_f32_16x16x32_bf16 v[32:35], v[146:149], v[198:201], v[32:35]
	v_mfma_f32_16x16x32_bf16 v[32:35], v[154:157], v[202:205], v[32:35]
	s_setprio 0
	s_setprio 1
	v_mfma_f32_16x16x32_bf16 v[28:31], v[158:161], v[174:177], v[28:31]
	v_mfma_f32_16x16x32_bf16 v[28:31], v[162:165], v[178:181], v[28:31]
	v_mfma_f32_16x16x32_bf16 v[24:27], v[166:169], v[174:177], v[24:27]
	v_mfma_f32_16x16x32_bf16 v[24:27], v[170:173], v[178:181], v[24:27]
	v_mfma_f32_16x16x32_bf16 v[20:23], v[158:161], v[182:185], v[20:23]
	v_mfma_f32_16x16x32_bf16 v[20:23], v[162:165], v[186:189], v[20:23]
	v_mfma_f32_16x16x32_bf16 v[16:19], v[166:169], v[182:185], v[16:19]
	v_mfma_f32_16x16x32_bf16 v[16:19], v[170:173], v[186:189], v[16:19]
	s_setprio 2
	s_barrier
	v_mfma_f32_16x16x32_bf16 v[12:15], v[158:161], v[190:193], v[12:15]
	v_mfma_f32_16x16x32_bf16 v[12:15], v[162:165], v[194:197], v[12:15]
	v_mfma_f32_16x16x32_bf16 v[8:11], v[166:169], v[190:193], v[8:11]
	v_mfma_f32_16x16x32_bf16 v[8:11], v[170:173], v[194:197], v[8:11]
	v_mfma_f32_16x16x32_bf16 v[4:7], v[158:161], v[198:201], v[4:7]
	v_mfma_f32_16x16x32_bf16 v[4:7], v[162:165], v[202:205], v[4:7]
	v_mfma_f32_16x16x32_bf16 v[0:3], v[166:169], v[198:201], v[0:3]
	v_mfma_f32_16x16x32_bf16 v[0:3], v[170:173], v[202:205], v[0:3]
	s_setprio 0
	s_add_i32 s46, s46, 2
	s_add_u32 s62, s62, 0x100
	s_addc_u32 s63, s63, 0
	s_add_u32 s44, s44, 0x100
	s_addc_u32 s45, s45, 0
	s_cmpk_gt_u32 s46, 0xa9
	s_cbranch_scc0 .LBB0_1034
	s_and_b64 vcc, exec, s[38:39]
	s_cbranch_vccz .LBB0_1037
	s_barrier

.LBB0_1180:
	ds_read_b128 v[112:115], v181
	ds_read_b128 v[116:119], v181 offset:1024
	ds_read_b128 v[128:131], v181 offset:2048
	ds_read_b128 v[142:145], v181 offset:3072
	ds_read_b128 v[146:149], v202
	ds_read_b128 v[150:153], v202 offset:1024
	ds_read_b128 v[154:157], v202 offset:2048
	ds_read_b128 v[168:171], v202 offset:3072
	s_add_u32 s49, s46, 0xfff80080
	s_addc_u32 s70, s47, -1
	s_cmp_eq_u32 s48, 28
	s_cselect_b32 s71, s39, s70
	s_cselect_b32 s70, s66, s49
	s_cselect_b32 s73, s37, s69
	s_cselect_b32 s72, s67, s68
	s_add_i32 m0, s45, 0xc000
	ds_read_b128 v[172:175], v203
	ds_read_b128 v[182:185], v203 offset:1024
	ds_read_b128 v[186:189], v203 offset:2048
	ds_read_b128 v[190:193], v203 offset:3072
	ds_read_b128 v[194:197], v203 offset:4096
	ds_read_b128 v[198:201], v203 offset:5120
	ds_read_b128 v[206:209], v203 offset:6144
	ds_read_b128 v[210:213], v203 offset:7168
	global_load_lds_dwordx4 v162, s[46:47]
	s_add_i32 m0, s45, 0xe000
	s_nop 0
	s_add_u32 s98, s46, s2
	s_addc_u32 s99, s47, s3
	global_load_lds_dwordx4 v162, s[98:99]
	s_waitcnt vmcnt(8)
	s_waitcnt lgkmcnt(0)
	s_barrier
	s_setprio 1
	s_waitcnt lgkmcnt(0)
	v_mfma_i32_16x16x64_i8 v[138:141], v[112:115], v[172:175], v[138:141]
	v_mfma_i32_16x16x64_i8 v[132:135], v[128:131], v[172:175], v[134:137]
	v_mfma_i32_16x16x64_i8 v[124:127], v[112:115], v[186:189], v[124:127]
	v_mfma_i32_16x16x64_i8 v[120:123], v[128:131], v[186:189], v[120:123]
	v_mfma_i32_16x16x64_i8 v[108:111], v[112:115], v[194:197], v[108:111]
	v_mfma_i32_16x16x64_i8 v[104:107], v[128:131], v[194:197], v[104:107]
	v_mfma_i32_16x16x64_i8 v[100:103], v[112:115], v[206:209], v[100:103]
	v_mfma_i32_16x16x64_i8 v[96:99], v[128:131], v[206:209], v[96:99]
	v_mfma_i32_16x16x64_i8 v[138:141], v[116:119], v[182:185], v[138:141]
	v_mfma_i32_16x16x64_i8 v[132:135], v[142:145], v[182:185], v[132:135]
	v_mfma_i32_16x16x64_i8 v[124:127], v[116:119], v[190:193], v[124:127]
	v_mfma_i32_16x16x64_i8 v[120:123], v[142:145], v[190:193], v[120:123]
	v_mfma_i32_16x16x64_i8 v[108:111], v[116:119], v[198:201], v[108:111]
	v_mfma_i32_16x16x64_i8 v[104:107], v[142:145], v[198:201], v[104:107]
	v_mfma_i32_16x16x64_i8 v[100:103], v[116:119], v[210:213], v[100:103]
	v_mfma_i32_16x16x64_i8 v[96:99], v[142:145], v[210:213], v[96:99]
	s_setprio 0
	s_setprio 1
	v_mfma_i32_16x16x64_i8 v[60:63], v[146:149], v[172:175], v[60:63]
	v_mfma_i32_16x16x64_i8 v[60:63], v[150:153], v[182:185], v[60:63]
	v_mfma_i32_16x16x64_i8 v[56:59], v[154:157], v[172:175], v[56:59]
	v_mfma_i32_16x16x64_i8 v[56:59], v[168:171], v[182:185], v[56:59]
	v_mfma_i32_16x16x64_i8 v[52:55], v[146:149], v[186:189], v[52:55]
	v_mfma_i32_16x16x64_i8 v[52:55], v[150:153], v[190:193], v[52:55]
	v_mfma_i32_16x16x64_i8 v[48:51], v[154:157], v[186:189], v[48:51]
	v_mfma_i32_16x16x64_i8 v[48:51], v[168:171], v[190:193], v[48:51]
	s_setprio 2
	s_barrier
	v_mfma_i32_16x16x64_i8 v[44:47], v[146:149], v[194:197], v[44:47]
	v_mfma_i32_16x16x64_i8 v[44:47], v[150:153], v[198:201], v[44:47]
	v_mfma_i32_16x16x64_i8 v[40:43], v[154:157], v[194:197], v[40:43]
	v_mfma_i32_16x16x64_i8 v[40:43], v[168:171], v[198:201], v[40:43]
	v_mfma_i32_16x16x64_i8 v[36:39], v[146:149], v[206:209], v[36:39]
	v_mfma_i32_16x16x64_i8 v[36:39], v[150:153], v[210:213], v[36:39]
	v_mfma_i32_16x16x64_i8 v[32:35], v[154:157], v[206:209], v[32:35]
	v_mfma_i32_16x16x64_i8 v[32:35], v[168:171], v[210:213], v[32:35]
	s_setprio 0
	s_add_i32 s49, s61, s33
	s_mov_b32 m0, s49
	ds_read_b128 v[172:175], v203 offset:16384
	ds_read_b128 v[182:185], v203 offset:17408
	ds_read_b128 v[186:189], v203 offset:18432
	ds_read_b128 v[190:193], v203 offset:19456
	ds_read_b128 v[194:197], v203 offset:20480
	ds_read_b128 v[198:201], v203 offset:21504
	ds_read_b128 v[206:209], v203 offset:22528
	ds_read_b128 v[210:213], v203 offset:23552
	global_load_lds_dwordx4 v160, s[72:73]
	s_add_i32 m0, s49, 0x2000
	s_add_i32 s49, s62, s33
	s_add_u32 s98, s72, s2
	s_addc_u32 s99, s73, s3
	global_load_lds_dwordx4 v160, s[98:99]
	s_mov_b32 m0, s49
	s_mov_b64 s[100:101], s[70:71]
	s_add_u32 s98, s72, s6
	s_addc_u32 s99, s73, s7
	global_load_lds_dwordx4 v160, s[98:99]
	s_add_i32 m0, s49, 0x2000
	s_nop 0
	s_add_u32 s98, s72, s8
	s_addc_u32 s99, s73, s9
	global_load_lds_dwordx4 v160, s[98:99]
	s_mov_b32 m0, s45
	s_nop 0
	global_load_lds_dwordx4 v158, s[70:71]
	s_mov_b32 m0, s50
	s_nop 0
	s_add_u32 s98, s70, s2
	s_addc_u32 s99, s71, s3
	global_load_lds_dwordx4 v158, s[98:99]
	s_waitcnt vmcnt(8)
	s_waitcnt lgkmcnt(0)
	s_barrier
	s_setprio 1
	s_waitcnt lgkmcnt(0)
	v_mfma_i32_16x16x64_i8 v[92:95], v[112:115], v[172:175], v[92:95]
	v_mfma_i32_16x16x64_i8 v[92:95], v[116:119], v[182:185], v[92:95]
	v_mfma_i32_16x16x64_i8 v[88:91], v[128:131], v[172:175], v[88:91]
	v_mfma_i32_16x16x64_i8 v[88:91], v[142:145], v[182:185], v[88:91]
	v_mfma_i32_16x16x64_i8 v[84:87], v[112:115], v[186:189], v[84:87]
	v_mfma_i32_16x16x64_i8 v[84:87], v[116:119], v[190:193], v[84:87]
	v_mfma_i32_16x16x64_i8 v[80:83], v[128:131], v[186:189], v[80:83]
	v_mfma_i32_16x16x64_i8 v[80:83], v[142:145], v[190:193], v[80:83]
	v_mfma_i32_16x16x64_i8 v[76:79], v[112:115], v[194:197], v[76:79]
	v_mfma_i32_16x16x64_i8 v[76:79], v[116:119], v[198:201], v[76:79]
	v_mfma_i32_16x16x64_i8 v[72:75], v[128:131], v[194:197], v[72:75]
	v_mfma_i32_16x16x64_i8 v[72:75], v[142:145], v[198:201], v[72:75]
	v_mfma_i32_16x16x64_i8 v[68:71], v[112:115], v[206:209], v[68:71]
	v_mfma_i32_16x16x64_i8 v[68:71], v[116:119], v[210:213], v[68:71]
	v_mfma_i32_16x16x64_i8 v[64:67], v[128:131], v[206:209], v[64:67]
	v_mfma_i32_16x16x64_i8 v[64:67], v[142:145], v[210:213], v[64:67]
	s_setprio 0
	s_setprio 1
	v_mfma_i32_16x16x64_i8 v[28:31], v[146:149], v[172:175], v[28:31]
	v_mfma_i32_16x16x64_i8 v[28:31], v[150:153], v[182:185], v[28:31]
	v_mfma_i32_16x16x64_i8 v[24:27], v[154:157], v[172:175], v[24:27]
	v_mfma_i32_16x16x64_i8 v[24:27], v[168:171], v[182:185], v[24:27]
	v_mfma_i32_16x16x64_i8 v[20:23], v[146:149], v[186:189], v[20:23]
	v_mfma_i32_16x16x64_i8 v[20:23], v[150:153], v[190:193], v[20:23]
	v_mfma_i32_16x16x64_i8 v[16:19], v[154:157], v[186:189], v[16:19]
	v_mfma_i32_16x16x64_i8 v[16:19], v[168:171], v[190:193], v[16:19]
	s_setprio 2
	s_barrier
	v_mfma_i32_16x16x64_i8 v[12:15], v[146:149], v[194:197], v[12:15]
	v_mfma_i32_16x16x64_i8 v[12:15], v[150:153], v[198:201], v[12:15]
	v_mfma_i32_16x16x64_i8 v[8:11], v[154:157], v[194:197], v[8:11]
	v_mfma_i32_16x16x64_i8 v[8:11], v[168:171], v[198:201], v[8:11]
	v_mfma_i32_16x16x64_i8 v[4:7], v[146:149], v[206:209], v[4:7]
	v_mfma_i32_16x16x64_i8 v[4:7], v[150:153], v[210:213], v[4:7]
	v_mfma_i32_16x16x64_i8 v[0:3], v[154:157], v[206:209], v[0:3]
	v_mfma_i32_16x16x64_i8 v[0:3], v[168:171], v[210:213], v[0:3]
	s_setprio 0
	s_add_i32 s49, 0, 0x18000
	v_add_u32_e32 v136, s49, v179
	s_add_i32 s70, 0, 0x1c000
	ds_read_b128 v[112:115], v136
	ds_read_b128 v[116:119], v136 offset:1024
	ds_read_b128 v[128:131], v136 offset:2048
	ds_read_b128 v[142:145], v136 offset:3072
	v_add_u32_e32 v136, s70, v179
	ds_read_b128 v[146:149], v136
	ds_read_b128 v[150:153], v136 offset:1024
	ds_read_b128 v[154:157], v136 offset:2048
	ds_read_b128 v[168:171], v136 offset:3072
	s_mov_b32 m0, s51
	ds_read_b128 v[172:175], v203 offset:32768
	ds_read_b128 v[182:185], v203 offset:33792
	ds_read_b128 v[186:189], v203 offset:34816
	ds_read_b128 v[190:193], v203 offset:35840
	ds_read_b128 v[194:197], v203 offset:36864
	ds_read_b128 v[198:201], v203 offset:37888
	ds_read_b128 v[206:209], v203 offset:38912
	ds_read_b128 v[210:213], v203 offset:39936
	s_add_u32 s98, s100, s6
	s_addc_u32 s99, s101, s7
	global_load_lds_dwordx4 v158, s[98:99]
	s_mov_b32 m0, s52
	s_nop 0
	s_add_u32 s98, s100, s8
	s_addc_u32 s99, s101, s9
	global_load_lds_dwordx4 v158, s[98:99]
	s_waitcnt vmcnt(8)
	s_waitcnt lgkmcnt(0)
	s_barrier
	s_setprio 1
	s_waitcnt lgkmcnt(0)
	v_mfma_i32_16x16x64_i8 v[136:139], v[112:115], v[172:175], v[138:141]
	v_mfma_i32_16x16x64_i8 v[132:135], v[128:131], v[172:175], v[132:135]
	v_mfma_i32_16x16x64_i8 v[124:127], v[112:115], v[186:189], v[124:127]
	v_mfma_i32_16x16x64_i8 v[120:123], v[128:131], v[186:189], v[120:123]
	v_mfma_i32_16x16x64_i8 v[108:111], v[112:115], v[194:197], v[108:111]
	v_mfma_i32_16x16x64_i8 v[104:107], v[128:131], v[194:197], v[104:107]
	v_mfma_i32_16x16x64_i8 v[100:103], v[112:115], v[206:209], v[100:103]
	v_mfma_i32_16x16x64_i8 v[96:99], v[128:131], v[206:209], v[96:99]
	v_mfma_i32_16x16x64_i8 v[138:141], v[116:119], v[182:185], v[136:139]
	v_mfma_i32_16x16x64_i8 v[134:137], v[142:145], v[182:185], v[132:135]
	v_mfma_i32_16x16x64_i8 v[124:127], v[116:119], v[190:193], v[124:127]
	v_mfma_i32_16x16x64_i8 v[120:123], v[142:145], v[190:193], v[120:123]
	v_mfma_i32_16x16x64_i8 v[108:111], v[116:119], v[198:201], v[108:111]
	v_mfma_i32_16x16x64_i8 v[104:107], v[142:145], v[198:201], v[104:107]
	v_mfma_i32_16x16x64_i8 v[100:103], v[116:119], v[210:213], v[100:103]
	v_mfma_i32_16x16x64_i8 v[96:99], v[142:145], v[210:213], v[96:99]
	s_setprio 0
	s_setprio 1
	v_mfma_i32_16x16x64_i8 v[60:63], v[146:149], v[172:175], v[60:63]
	v_mfma_i32_16x16x64_i8 v[60:63], v[150:153], v[182:185], v[60:63]
	v_mfma_i32_16x16x64_i8 v[56:59], v[154:157], v[172:175], v[56:59]
	v_mfma_i32_16x16x64_i8 v[56:59], v[168:171], v[182:185], v[56:59]
	v_mfma_i32_16x16x64_i8 v[52:55], v[146:149], v[186:189], v[52:55]
	v_mfma_i32_16x16x64_i8 v[52:55], v[150:153], v[190:193], v[52:55]
	v_mfma_i32_16x16x64_i8 v[48:51], v[154:157], v[186:189], v[48:51]
	v_mfma_i32_16x16x64_i8 v[48:51], v[168:171], v[190:193], v[48:51]
	s_setprio 2
	s_barrier
	v_mfma_i32_16x16x64_i8 v[44:47], v[146:149], v[194:197], v[44:47]
	v_mfma_i32_16x16x64_i8 v[44:47], v[150:153], v[198:201], v[44:47]
	v_mfma_i32_16x16x64_i8 v[40:43], v[154:157], v[194:197], v[40:43]
	v_mfma_i32_16x16x64_i8 v[40:43], v[168:171], v[198:201], v[40:43]
	v_mfma_i32_16x16x64_i8 v[36:39], v[146:149], v[206:209], v[36:39]
	v_mfma_i32_16x16x64_i8 v[36:39], v[150:153], v[210:213], v[36:39]
	v_mfma_i32_16x16x64_i8 v[32:35], v[154:157], v[206:209], v[32:35]
	v_mfma_i32_16x16x64_i8 v[32:35], v[168:171], v[210:213], v[32:35]
	s_setprio 0
	s_add_i32 s49, s49, s33
	s_mov_b32 m0, s49
	ds_read_b128 v[172:175], v203 offset:49152
	ds_read_b128 v[182:185], v203 offset:50176
	ds_read_b128 v[186:189], v203 offset:51200
	ds_read_b128 v[190:193], v203 offset:52224
	ds_read_b128 v[194:197], v203 offset:53248
	ds_read_b128 v[198:201], v203 offset:54272
	ds_read_b128 v[206:209], v203 offset:55296
	ds_read_b128 v[210:213], v203 offset:56320
	s_add_u32 s98, s72, s16
	s_addc_u32 s99, s73, s17
	global_load_lds_dwordx4 v160, s[98:99]
	s_add_i32 m0, s49, 0x2000
	s_add_i32 s49, s70, s33
	s_add_u32 s98, s72, s18
	s_addc_u32 s99, s73, s19
	global_load_lds_dwordx4 v160, s[98:99]
	s_mov_b32 m0, s49
	s_nop 0
	s_add_u32 s98, s72, s20
	s_addc_u32 s99, s73, s21
	global_load_lds_dwordx4 v160, s[98:99]
	s_add_i32 m0, s49, 0x2000
	s_nop 0
	s_add_u32 s98, s72, s30
	s_addc_u32 s99, s73, s31
	global_load_lds_dwordx4 v160, s[98:99]
	s_mov_b32 m0, s54
	s_nop 0
	s_add_u32 s98, s100, s16
	s_addc_u32 s99, s101, s17
	global_load_lds_dwordx4 v158, s[98:99]
	s_mov_b32 m0, s55
	s_nop 0
	s_add_u32 s98, s100, s18
	s_addc_u32 s99, s101, s19
	global_load_lds_dwordx4 v158, s[98:99]
	s_waitcnt vmcnt(8)
	s_waitcnt lgkmcnt(0)
	s_barrier
	s_setprio 1
	s_waitcnt lgkmcnt(0)
	v_mfma_i32_16x16x64_i8 v[92:95], v[112:115], v[172:175], v[92:95]
	v_mfma_i32_16x16x64_i8 v[92:95], v[116:119], v[182:185], v[92:95]
	v_mfma_i32_16x16x64_i8 v[88:91], v[128:131], v[172:175], v[88:91]
	v_mfma_i32_16x16x64_i8 v[88:91], v[142:145], v[182:185], v[88:91]
	v_mfma_i32_16x16x64_i8 v[84:87], v[112:115], v[186:189], v[84:87]
	v_mfma_i32_16x16x64_i8 v[84:87], v[116:119], v[190:193], v[84:87]
	v_mfma_i32_16x16x64_i8 v[80:83], v[128:131], v[186:189], v[80:83]
	v_mfma_i32_16x16x64_i8 v[80:83], v[142:145], v[190:193], v[80:83]
	v_mfma_i32_16x16x64_i8 v[76:79], v[112:115], v[194:197], v[76:79]
	v_mfma_i32_16x16x64_i8 v[76:79], v[116:119], v[198:201], v[76:79]
	v_mfma_i32_16x16x64_i8 v[72:75], v[128:131], v[194:197], v[72:75]
	v_mfma_i32_16x16x64_i8 v[72:75], v[142:145], v[198:201], v[72:75]
	v_mfma_i32_16x16x64_i8 v[68:71], v[112:115], v[206:209], v[68:71]
	v_mfma_i32_16x16x64_i8 v[68:71], v[116:119], v[210:213], v[68:71]
	v_mfma_i32_16x16x64_i8 v[64:67], v[128:131], v[206:209], v[64:67]
	v_mfma_i32_16x16x64_i8 v[64:67], v[142:145], v[210:213], v[64:67]
	s_setprio 0
	s_setprio 1
	v_mfma_i32_16x16x64_i8 v[28:31], v[146:149], v[172:175], v[28:31]
	v_mfma_i32_16x16x64_i8 v[28:31], v[150:153], v[182:185], v[28:31]
	v_mfma_i32_16x16x64_i8 v[24:27], v[154:157], v[172:175], v[24:27]
	v_mfma_i32_16x16x64_i8 v[24:27], v[168:171], v[182:185], v[24:27]
	v_mfma_i32_16x16x64_i8 v[20:23], v[146:149], v[186:189], v[20:23]
	v_mfma_i32_16x16x64_i8 v[20:23], v[150:153], v[190:193], v[20:23]
	v_mfma_i32_16x16x64_i8 v[16:19], v[154:157], v[186:189], v[16:19]
	v_mfma_i32_16x16x64_i8 v[16:19], v[168:171], v[190:193], v[16:19]
	s_setprio 2
	s_barrier
	v_mfma_i32_16x16x64_i8 v[12:15], v[146:149], v[194:197], v[12:15]
	v_mfma_i32_16x16x64_i8 v[12:15], v[150:153], v[198:201], v[12:15]
	v_mfma_i32_16x16x64_i8 v[8:11], v[154:157], v[194:197], v[8:11]
	v_mfma_i32_16x16x64_i8 v[8:11], v[168:171], v[198:201], v[8:11]
	v_mfma_i32_16x16x64_i8 v[4:7], v[146:149], v[206:209], v[4:7]
	v_mfma_i32_16x16x64_i8 v[4:7], v[150:153], v[210:213], v[4:7]
	v_mfma_i32_16x16x64_i8 v[0:3], v[154:157], v[206:209], v[0:3]
	v_mfma_i32_16x16x64_i8 v[0:3], v[168:171], v[210:213], v[0:3]
	s_setprio 0
	s_add_i32 s48, s48, 2
	s_add_u32 s68, s68, 0x100
	s_addc_u32 s69, s69, 0
	s_add_u32 s46, s46, 0x100
	s_addc_u32 s47, s47, 0
	s_cmp_gt_u32 s48, 29
	s_cbranch_scc0 .LBB0_1180
	s_and_b64 vcc, exec, s[34:35]
	s_cbranch_vccz .LBB0_1183
	s_barrier
